# P1 unit-transition drain removed; gMLP epilogue u/gate/bias loads hoisted with counted waits
# speedup vs baseline: 1.0324x; 1.0034x over previous
; template <int MODE>
; __device__ __forceinline__ void gemm_phase(LAS unsigned char* lds, const Params& p, int l, int single) {
;     ...
;         if (!has_next) break;
; #pragma unroll
;         for (int a = 0; a < 2; ++a)
; #pragma unroll
;             for (int b = 0; b < 2; ++b)
; #pragma unroll
;                 for (int m = 0; m < 4; ++m)
; #pragma unroll
;                     for (int n = 0; n < 2; ++n) acc[a][b][m][n] = (f32x4){0.f, 0.f, 0.f, 0.f};
;         cur = nxt; cA = nA; cB = nB; ++ui;
.LBB0_180:
	s_add_u32 s40, s40, 0x80080
	s_addc_u32 s41, s41, 0
	s_add_u32 s15, s20, 0x100
	v_mov_b32_e32 v2, 0
	s_addc_u32 s17, s21, 0
	s_mov_b32 s22, -2
	v_mov_b32_e32 v3, v2
	v_mov_b32_e32 v4, v2
	v_mov_b32_e32 v5, v2
	v_mov_b32_e32 v6, v2
	v_mov_b32_e32 v7, v2
	v_mov_b32_e32 v8, v2
	v_mov_b32_e32 v9, v2
	v_mov_b32_e32 v10, v2
	v_mov_b32_e32 v11, v2
	v_mov_b32_e32 v12, v2
	v_mov_b32_e32 v13, v2
	v_mov_b32_e32 v14, v2
	v_mov_b32_e32 v15, v2
	v_mov_b32_e32 v16, v2
	v_mov_b32_e32 v17, v2
	v_mov_b32_e32 v18, v2
	v_mov_b32_e32 v19, v2
	v_mov_b32_e32 v20, v2
	v_mov_b32_e32 v21, v2
	v_mov_b32_e32 v22, v2
	v_mov_b32_e32 v23, v2
	v_mov_b32_e32 v24, v2
	v_mov_b32_e32 v25, v2
	v_mov_b32_e32 v26, v2
	v_mov_b32_e32 v27, v2
	v_mov_b32_e32 v28, v2
	v_mov_b32_e32 v29, v2
	v_mov_b32_e32 v30, v2
	v_mov_b32_e32 v31, v2
	v_mov_b32_e32 v32, v2
	v_mov_b32_e32 v33, v2
	v_mov_b32_e32 v66, v2
	v_mov_b32_e32 v67, v2
	v_mov_b32_e32 v68, v2
	v_mov_b32_e32 v69, v2
	v_mov_b32_e32 v70, v2
	v_mov_b32_e32 v71, v2
	v_mov_b32_e32 v72, v2
	v_mov_b32_e32 v73, v2
	v_mov_b32_e32 v74, v2
	v_mov_b32_e32 v75, v2
	v_mov_b32_e32 v76, v2
	v_mov_b32_e32 v77, v2
	v_mov_b32_e32 v78, v2
	v_mov_b32_e32 v79, v2
	v_mov_b32_e32 v80, v2
	v_mov_b32_e32 v81, v2
	v_mov_b32_e32 v82, v2
	v_mov_b32_e32 v83, v2
	v_mov_b32_e32 v84, v2
	v_mov_b32_e32 v85, v2
	v_mov_b32_e32 v86, v2
	v_mov_b32_e32 v87, v2
	v_mov_b32_e32 v88, v2
	v_mov_b32_e32 v89, v2
	v_mov_b32_e32 v90, v2
	v_mov_b32_e32 v91, v2
	v_mov_b32_e32 v92, v2
	v_mov_b32_e32 v93, v2
	v_mov_b32_e32 v94, v2
	v_mov_b32_e32 v95, v2
	v_mov_b32_e32 v96, v2
	v_mov_b32_e32 v97, v2
	v_mov_b32_e32 v34, v2
	v_mov_b32_e32 v35, v2
	v_mov_b32_e32 v36, v2
	v_mov_b32_e32 v37, v2
	v_mov_b32_e32 v38, v2
	v_mov_b32_e32 v39, v2
	v_mov_b32_e32 v40, v2
	v_mov_b32_e32 v41, v2
	v_mov_b32_e32 v42, v2
	v_mov_b32_e32 v43, v2
	v_mov_b32_e32 v44, v2
	v_mov_b32_e32 v45, v2
	v_mov_b32_e32 v46, v2
	v_mov_b32_e32 v47, v2
	v_mov_b32_e32 v48, v2
	v_mov_b32_e32 v49, v2
	v_mov_b32_e32 v50, v2
	v_mov_b32_e32 v51, v2
	v_mov_b32_e32 v52, v2
	v_mov_b32_e32 v53, v2
	v_mov_b32_e32 v54, v2
	v_mov_b32_e32 v55, v2
	v_mov_b32_e32 v56, v2
	v_mov_b32_e32 v57, v2
	v_mov_b32_e32 v58, v2
	v_mov_b32_e32 v59, v2
	v_mov_b32_e32 v60, v2
	v_mov_b32_e32 v61, v2
	v_mov_b32_e32 v62, v2
	v_mov_b32_e32 v63, v2
	v_mov_b32_e32 v64, v2
	v_mov_b32_e32 v65, v2
	v_mov_b32_e32 v98, v2
	v_mov_b32_e32 v99, v2
	v_mov_b32_e32 v100, v2
	v_mov_b32_e32 v101, v2
	v_mov_b32_e32 v102, v2
	v_mov_b32_e32 v103, v2
	v_mov_b32_e32 v104, v2
	v_mov_b32_e32 v105, v2
	v_mov_b32_e32 v106, v2
	v_mov_b32_e32 v107, v2
	v_mov_b32_e32 v108, v2
	v_mov_b32_e32 v109, v2
	v_mov_b32_e32 v110, v2
	v_mov_b32_e32 v111, v2
	v_mov_b32_e32 v112, v2
	v_mov_b32_e32 v113, v2
	v_mov_b32_e32 v114, v2
	v_mov_b32_e32 v115, v2
	v_mov_b32_e32 v116, v2
	v_mov_b32_e32 v117, v2
	v_mov_b32_e32 v118, v2
	v_mov_b32_e32 v119, v2
	v_mov_b32_e32 v120, v2
	v_mov_b32_e32 v121, v2
	v_mov_b32_e32 v122, v2
	v_mov_b32_e32 v123, v2
	v_mov_b32_e32 v124, v2
	v_mov_b32_e32 v125, v2
	v_mov_b32_e32 v126, v2
	v_mov_b32_e32 v127, v2
	v_mov_b32_e32 v128, v2
	v_mov_b32_e32 v129, v2

; __device__ __forceinline__ unsigned cvt_pk_bf16(float lo, float hi) { unsigned r; asm("v_cvt_pk_bf16_f32 %0, %1, %2" : "=v"(r) : "v"(lo), "v"(hi)); return r; }
; __device__ __forceinline__ float bflo(unsigned w) { return __uint_as_float(w << 16); }
; __device__ __forceinline__ float bfhi(unsigned w) { return __uint_as_float(w & 0xffff0000u); }
; __device__ __forceinline__ float silu(float x) { return x / (1.f + __expf(-x)); }
; __device__ __forceinline__ void gmlp_item(const Params& p, int l, int mc, int g, LAS unsigned char* lds) {
;     ...
;     const float* bsp = p.b_s + (size_t)(l * 4 + g) * 128;
; #pragma unroll
;     for (int tt = 0; tt < 8; ++tt) {
;         if (tt < ntt) {
;             const int tok = tok0 + tt * 16 + fr; const float bs = bsp[tt * 16 + fr];
; #pragma unroll
;             for (int ct = 0; ct < 2; ++ct) {
;                 const int cb = g * 256 + w * 32 + ct * 16 + fq * 4;
;                 const u32x2 uu = *(const u32x2*)((const u16*)(ws + WS_ZU) + (size_t)tok * 1024 + cb);
;                 const u32x2 gg = *(const u32x2*)((const u16*)(ws + WS_ZGB) + (size_t)tok * 1024 + cb);
;                 const float o0 = bflo(uu.x) * (acc[ct][tt][0] + bs) * silu(bflo(gg.x));
;                 const float o1 = bfhi(uu.x) * (acc[ct][tt][1] + bs) * silu(bfhi(gg.x));
;                 const float o2 = bflo(uu.y) * (acc[ct][tt][2] + bs) * silu(bflo(gg.y));
;                 const float o3 = bfhi(uu.y) * (acc[ct][tt][3] + bs) * silu(bfhi(gg.y));
;                 u32x2 wv; wv.x = cvt_pk_bf16(o0, o1); wv.y = cvt_pk_bf16(o2, o3);
;                 *(u32x2*)((u16*)(ws + WS_OBUF) + (size_t)tok * 2048 + 1024 + cb) = wv;
;             }
;         }
;     }
.LBB0_766:
	v_or_b32_e32 v0, s2, v161
	v_add_u32_e32 v2, s6, v84
	v_lshrrev_b32_e32 v3, 2, v160
	s_waitcnt lgkmcnt(0)
	v_and_or_b32 v74, v3, 12, v2
	v_lshlrev_b64 v[2:3], 11, v[0:1]
	v_lshl_add_u64 v[72:73], s[86:87], 0, v[2:3]
	v_lshl_add_u64 v[76:77], s[34:35], 0, v[2:3]
	v_lshlrev_b64 v[2:3], 12, v[0:1]
	s_lshl_b64 s[0:1], s[0:1], 9
	v_lshl_add_u64 v[2:3], s[58:59], 0, v[2:3]
	s_mov_b64 s[10:11], 0x2958c800
	v_ashrrev_i32_e32 v75, 31, v74
	s_add_u32 s0, s74, s0
	v_lshl_add_u64 v[70:71], v[2:3], 0, s[10:11]
	v_lshlrev_b64 v[2:3], 1, v[74:75]
	s_addc_u32 s1, s75, s1
	v_lshlrev_b32_e32 v68, 2, v161
	v_lshl_add_u64 v[78:79], v[72:73], 0, v[2:3]
	v_lshl_add_u64 v[72:73], v[76:77], 0, v[2:3]
	s_mov_b64 s[98:99], 0x8000
	v_mov_b32_e32 v224, v78
	v_mov_b32_e32 v225, v79
	v_mov_b32_e32 v226, v72
	v_mov_b32_e32 v227, v73
	global_load_dword v178, v68, s[0:1]
	global_load_dwordx2 v[182:183], v[224:225], off
	global_load_dwordx2 v[208:209], v[226:227], off
	global_load_dwordx2 v[184:185], v[224:225], off offset:32
	global_load_dwordx2 v[210:211], v[226:227], off offset:32
	v_lshl_add_u64 v[224:225], v[224:225], 0, s[98:99]
	v_lshl_add_u64 v[226:227], v[226:227], 0, s[98:99]
	global_load_dword v179, v68, s[0:1] offset:64
	global_load_dwordx2 v[186:187], v[224:225], off
	global_load_dwordx2 v[212:213], v[226:227], off
	global_load_dwordx2 v[188:189], v[224:225], off offset:32
	global_load_dwordx2 v[214:215], v[226:227], off offset:32
	v_lshl_add_u64 v[224:225], v[224:225], 0, s[98:99]
	v_lshl_add_u64 v[226:227], v[226:227], 0, s[98:99]
	global_load_dword v180, v68, s[0:1] offset:128
	global_load_dwordx2 v[190:191], v[224:225], off
	global_load_dwordx2 v[216:217], v[226:227], off
	global_load_dwordx2 v[192:193], v[224:225], off offset:32
	global_load_dwordx2 v[218:219], v[226:227], off offset:32
	v_lshl_add_u64 v[224:225], v[224:225], 0, s[98:99]
	v_lshl_add_u64 v[226:227], v[226:227], 0, s[98:99]
	global_load_dword v181, v68, s[0:1] offset:192
	global_load_dwordx2 v[194:195], v[224:225], off
	global_load_dwordx2 v[220:221], v[226:227], off
	global_load_dwordx2 v[196:197], v[224:225], off offset:32
	global_load_dwordx2 v[222:223], v[226:227], off offset:32
	v_lshl_add_u64 v[224:225], v[224:225], 0, s[98:99]
	v_lshl_add_u64 v[226:227], v[226:227], 0, s[98:99]
	v_mov_b32_e32 v228, v224
	v_mov_b32_e32 v229, v225
	v_mov_b32_e32 v230, v226
	v_mov_b32_e32 v231, v227
	v_mov_b32_e32 v232, v68
	v_mov_b32_e32 v233, 0
	v_lshl_add_u64 v[232:233], s[0:1], 0, v[232:233]
	v_lshl_add_u64 v[232:233], v[232:233], 0, 64
	v_lshl_add_u64 v[232:233], v[232:233], 0, 64
	v_lshl_add_u64 v[232:233], v[232:233], 0, 64
	v_lshl_add_u64 v[232:233], v[232:233], 0, 64
	s_waitcnt vmcnt(19)
	v_mov_b32_e32 v69, v178
	v_add_f32_e32 v64, v64, v69
	s_waitcnt vmcnt(18)
	v_mov_b32_e32 v80, v182
	v_mov_b32_e32 v81, v183
	v_lshlrev_b32_e32 v75, 16, v80
	v_mul_f32_e32 v64, v64, v75
	s_waitcnt vmcnt(17)
	v_mov_b32_e32 v76, v208
	v_mov_b32_e32 v77, v209
	v_lshlrev_b32_e32 v75, 16, v76
	v_mul_f32_e32 v82, 0xbfb8aa3b, v75
	v_exp_f32_e32 v82, v82
	v_add_f32_e32 v65, v65, v69
	v_add_f32_e32 v66, v66, v69
	v_add_f32_e32 v67, v67, v69
	v_add_f32_e32 v82, 1.0, v82
	v_div_scale_f32 v83, s[6:7], v82, v82, v75
	v_rcp_f32_e32 v84, v83
	v_add_f32_e32 v60, v60, v69
	v_add_f32_e32 v61, v61, v69
	v_add_f32_e32 v62, v62, v69
	v_fma_f32 v85, -v83, v84, 1.0
	v_fmac_f32_e32 v84, v85, v84
	v_div_scale_f32 v85, vcc, v75, v82, v75
	v_mul_f32_e32 v86, v85, v84
	v_fma_f32 v87, -v83, v86, v85
	v_fmac_f32_e32 v86, v87, v84
	v_fma_f32 v83, -v83, v86, v85
	v_div_fmas_f32 v83, v83, v84, v86
	v_div_fixup_f32 v75, v83, v82, v75
	v_mul_f32_e32 v64, v64, v75
	v_and_b32_e32 v75, 0xffff0000, v80
	v_mul_f32_e32 v65, v65, v75
	v_and_b32_e32 v75, 0xffff0000, v76
	v_mul_f32_e32 v76, 0xbfb8aa3b, v75
	v_exp_f32_e32 v76, v76
	v_add_f32_e32 v63, v63, v69
	v_add_f32_e32 v76, 1.0, v76
	v_div_scale_f32 v80, s[6:7], v76, v76, v75
	v_rcp_f32_e32 v82, v80
	s_nop 0
	v_fma_f32 v83, -v80, v82, 1.0
	v_fmac_f32_e32 v82, v83, v82
	v_div_scale_f32 v83, vcc, v75, v76, v75
	v_mul_f32_e32 v84, v83, v82
	v_fma_f32 v85, -v80, v84, v83
	v_fmac_f32_e32 v84, v85, v82
	v_fma_f32 v80, -v80, v84, v83
	v_div_fmas_f32 v80, v80, v82, v84
	v_div_fixup_f32 v75, v80, v76, v75
	v_mul_f32_e32 v65, v65, v75
	v_lshlrev_b32_e32 v75, 16, v81
	v_mul_f32_e32 v66, v66, v75
	v_lshlrev_b32_e32 v75, 16, v77
	v_mul_f32_e32 v76, 0xbfb8aa3b, v75
	v_exp_f32_e32 v76, v76
	v_cvt_pk_bf16_f32 v64, v64, v65
	s_nop 0
	v_add_f32_e32 v76, 1.0, v76
	v_div_scale_f32 v80, s[6:7], v76, v76, v75
	v_rcp_f32_e32 v82, v80
	s_nop 0
	v_fma_f32 v83, -v80, v82, 1.0
	v_fmac_f32_e32 v82, v83, v82
	v_div_scale_f32 v83, vcc, v75, v76, v75
	v_mul_f32_e32 v84, v83, v82
	v_fma_f32 v85, -v80, v84, v83
	v_fmac_f32_e32 v84, v85, v82
	v_fma_f32 v80, -v80, v84, v83
	v_div_fmas_f32 v80, v80, v82, v84
	v_div_fixup_f32 v75, v80, v76, v75
	v_mul_f32_e32 v66, v66, v75
	v_and_b32_e32 v75, 0xffff0000, v81
	v_mul_f32_e32 v67, v67, v75
	v_and_b32_e32 v75, 0xffff0000, v77
	v_mul_f32_e32 v76, 0xbfb8aa3b, v75
	v_exp_f32_e32 v76, v76
	s_nop 0
	v_add_f32_e32 v76, 1.0, v76
	v_div_scale_f32 v77, s[6:7], v76, v76, v75
	v_rcp_f32_e32 v80, v77
	s_nop 0
	v_fma_f32 v81, -v77, v80, 1.0
	v_fmac_f32_e32 v80, v81, v80
	v_div_scale_f32 v81, vcc, v75, v76, v75
	v_mul_f32_e32 v82, v81, v80
	v_fma_f32 v83, -v77, v82, v81
	v_fmac_f32_e32 v82, v83, v80
	v_fma_f32 v77, -v77, v82, v81
	v_div_fmas_f32 v77, v77, v80, v82
	v_div_fixup_f32 v75, v77, v76, v75
	v_mul_f32_e32 v67, v67, v75
	v_cvt_pk_bf16_f32 v65, v66, v67
	v_lshl_add_u64 v[66:67], v[70:71], 0, v[2:3]
	global_store_dwordx2 v[66:67], v[64:65], off
	s_nop 0
	v_or_b32_e32 v64, 16, v74
	v_ashrrev_i32_e32 v65, 31, v64
	s_waitcnt vmcnt(17)
; __device__ __forceinline__ unsigned cvt_pk_bf16(float lo, float hi) { unsigned r; asm("v_cvt_pk_bf16_f32 %0, %1, %2" : "=v"(r) : "v"(lo), "v"(hi)); return r; }
; __device__ __forceinline__ float bflo(unsigned w) { return __uint_as_float(w << 16); }
; __device__ __forceinline__ float bfhi(unsigned w) { return __uint_as_float(w & 0xffff0000u); }
; __device__ __forceinline__ float silu(float x) { return x / (1.f + __expf(-x)); }
; __device__ __forceinline__ void gmlp_item(const Params& p, int l, int mc, int g, LAS unsigned char* lds) {
;     ...
;     const float* bsp = p.b_s + (size_t)(l * 4 + g) * 128;
; #pragma unroll
;     for (int tt = 0; tt < 8; ++tt) {
;         if (tt < ntt) {
;             const int tok = tok0 + tt * 16 + fr; const float bs = bsp[tt * 16 + fr];
; #pragma unroll
;             for (int ct = 0; ct < 2; ++ct) {
;                 const int cb = g * 256 + w * 32 + ct * 16 + fq * 4;
;                 const u32x2 uu = *(const u32x2*)((const u16*)(ws + WS_ZU) + (size_t)tok * 1024 + cb);
;                 const u32x2 gg = *(const u32x2*)((const u16*)(ws + WS_ZGB) + (size_t)tok * 1024 + cb);
;                 const float o0 = bflo(uu.x) * (acc[ct][tt][0] + bs) * silu(bflo(gg.x));
;                 const float o1 = bfhi(uu.x) * (acc[ct][tt][1] + bs) * silu(bfhi(gg.x));
;                 const float o2 = bflo(uu.y) * (acc[ct][tt][2] + bs) * silu(bflo(gg.y));
;                 const float o3 = bfhi(uu.y) * (acc[ct][tt][3] + bs) * silu(bfhi(gg.y));
;                 u32x2 wv; wv.x = cvt_pk_bf16(o0, o1); wv.y = cvt_pk_bf16(o2, o3);
;                 *(u32x2*)((u16*)(ws + WS_OBUF) + (size_t)tok * 2048 + 1024 + cb) = wv;
;             }
;         }
;     }
	v_mov_b32_e32 v66, v184
	v_mov_b32_e32 v67, v185
	v_lshlrev_b32_e32 v74, 16, v66
	v_mul_f32_e32 v60, v60, v74
	s_waitcnt vmcnt(16)
	v_mov_b32_e32 v72, v210
	v_mov_b32_e32 v73, v211
	v_lshlrev_b32_e32 v74, 16, v72
	v_mul_f32_e32 v75, 0xbfb8aa3b, v74
	v_exp_f32_e32 v75, v75
	v_and_b32_e32 v66, 0xffff0000, v66
	v_mul_f32_e32 v61, v61, v66
	v_and_b32_e32 v66, 0xffff0000, v72
	v_add_f32_e32 v75, 1.0, v75
	v_div_scale_f32 v76, s[6:7], v75, v75, v74
	v_rcp_f32_e32 v77, v76
	v_mul_f32_e32 v72, 0xbfb8aa3b, v66
	v_exp_f32_e32 v72, v72
	v_fma_f32 v78, -v76, v77, 1.0
	v_fmac_f32_e32 v77, v78, v77
	v_div_scale_f32 v78, vcc, v74, v75, v74
	v_mul_f32_e32 v79, v78, v77
	v_fma_f32 v80, -v76, v79, v78
	v_fmac_f32_e32 v79, v80, v77
	v_fma_f32 v76, -v76, v79, v78
	v_div_fmas_f32 v76, v76, v77, v79
	v_div_fixup_f32 v74, v76, v75, v74
	v_add_f32_e32 v72, 1.0, v72
	v_mul_f32_e32 v60, v60, v74
	v_div_scale_f32 v74, s[6:7], v72, v72, v66
	v_rcp_f32_e32 v75, v74
	s_nop 0
	v_fma_f32 v76, -v74, v75, 1.0
	v_fmac_f32_e32 v75, v76, v75
	v_div_scale_f32 v76, vcc, v66, v72, v66
	v_mul_f32_e32 v77, v76, v75
	v_fma_f32 v78, -v74, v77, v76
	v_fmac_f32_e32 v77, v78, v75
	v_fma_f32 v74, -v74, v77, v76
	v_div_fmas_f32 v74, v74, v75, v77
	v_div_fixup_f32 v66, v74, v72, v66
	v_mul_f32_e32 v61, v61, v66
	v_lshlrev_b32_e32 v66, 16, v67
	v_mul_f32_e32 v62, v62, v66
	v_lshlrev_b32_e32 v66, 16, v73
	v_mul_f32_e32 v72, 0xbfb8aa3b, v66
	v_exp_f32_e32 v72, v72
	s_nop 0
	v_add_f32_e32 v72, 1.0, v72
	v_div_scale_f32 v74, s[6:7], v72, v72, v66
	v_rcp_f32_e32 v75, v74
	s_nop 0
	v_fma_f32 v76, -v74, v75, 1.0
	v_fmac_f32_e32 v75, v76, v75
	v_div_scale_f32 v76, vcc, v66, v72, v66
	v_mul_f32_e32 v77, v76, v75
	v_fma_f32 v78, -v74, v77, v76
	v_fmac_f32_e32 v77, v78, v75
	v_fma_f32 v74, -v74, v77, v76
	v_div_fmas_f32 v74, v74, v75, v77
	v_div_fixup_f32 v66, v74, v72, v66
	v_mul_f32_e32 v66, v62, v66
	v_and_b32_e32 v62, 0xffff0000, v67
	v_mul_f32_e32 v62, v63, v62
	v_and_b32_e32 v63, 0xffff0000, v73
	v_mul_f32_e32 v67, 0xbfb8aa3b, v63
	v_exp_f32_e32 v67, v67
	s_nop 0
	v_add_f32_e32 v67, 1.0, v67
	v_div_scale_f32 v69, s[6:7], v67, v67, v63
	v_rcp_f32_e32 v72, v69
	s_nop 0
	v_fma_f32 v73, -v69, v72, 1.0
	v_fmac_f32_e32 v72, v73, v72
	v_div_scale_f32 v73, vcc, v63, v67, v63
	v_mul_f32_e32 v74, v73, v72
	v_fma_f32 v75, -v69, v74, v73
	v_fmac_f32_e32 v74, v75, v72
	v_fma_f32 v69, -v69, v74, v73
	v_div_fmas_f32 v69, v69, v72, v74
	v_div_fixup_f32 v63, v69, v67, v63
	v_mul_f32_e32 v63, v62, v63
	v_cvt_pk_bf16_f32 v62, v60, v61
	v_lshlrev_b64 v[60:61], 1, v[64:65]
	v_cvt_pk_bf16_f32 v63, v66, v63
	v_lshl_add_u64 v[64:65], v[70:71], 0, v[60:61]
	global_store_dwordx2 v[64:65], v[62:63], off
	v_or_b32_e32 v62, 16, v0
	v_mov_b32_e32 v63, v1
	v_lshlrev_b64 v[64:65], 11, v[62:63]
	v_lshl_add_u64 v[70:71], s[86:87], 0, v[64:65]
	v_lshl_add_u64 v[64:65], s[34:35], 0, v[64:65]
	v_lshl_add_u64 v[70:71], v[70:71], 0, v[2:3]
	v_lshl_add_u64 v[64:65], v[64:65], 0, v[2:3]
	v_lshlrev_b64 v[62:63], 12, v[62:63]
	v_lshl_add_u64 v[62:63], s[58:59], 0, v[62:63]
	v_lshl_add_u64 v[62:63], v[62:63], 0, s[10:11]
	s_waitcnt vmcnt(16)
	v_mov_b32_e32 v66, v179
	v_add_f32_e32 v56, v56, v66
	s_waitcnt vmcnt(15)
	v_mov_b32_e32 v72, v186
	v_mov_b32_e32 v73, v187
	v_lshlrev_b32_e32 v67, 16, v72
	v_mul_f32_e32 v56, v56, v67
	s_waitcnt vmcnt(14)
	v_mov_b32_e32 v74, v212
	v_mov_b32_e32 v75, v213
	v_lshlrev_b32_e32 v67, 16, v74
	v_mul_f32_e32 v69, 0xbfb8aa3b, v67
	v_exp_f32_e32 v69, v69
	v_add_f32_e32 v57, v57, v66
	v_add_f32_e32 v58, v58, v66
	v_add_f32_e32 v59, v59, v66
	v_add_f32_e32 v69, 1.0, v69
	v_div_scale_f32 v76, s[6:7], v69, v69, v67
	v_rcp_f32_e32 v77, v76
	v_add_f32_e32 v52, v52, v66
	v_add_f32_e32 v53, v53, v66
	v_add_f32_e32 v54, v54, v66
	v_fma_f32 v78, -v76, v77, 1.0
	v_fmac_f32_e32 v77, v78, v77
	v_div_scale_f32 v78, vcc, v67, v69, v67
	v_mul_f32_e32 v79, v78, v77
	v_fma_f32 v80, -v76, v79, v78
	v_fmac_f32_e32 v79, v80, v77
	v_fma_f32 v76, -v76, v79, v78
	v_div_fmas_f32 v76, v76, v77, v79
	v_div_fixup_f32 v67, v76, v69, v67
	v_mul_f32_e32 v56, v56, v67
	v_and_b32_e32 v67, 0xffff0000, v72
	v_mul_f32_e32 v57, v57, v67
	v_and_b32_e32 v67, 0xffff0000, v74
	v_mul_f32_e32 v69, 0xbfb8aa3b, v67
	v_exp_f32_e32 v69, v69
	v_add_f32_e32 v55, v55, v66
	v_add_f32_e32 v69, 1.0, v69
	v_div_scale_f32 v72, s[6:7], v69, v69, v67
	v_rcp_f32_e32 v74, v72
	s_nop 0
	v_fma_f32 v76, -v72, v74, 1.0
	v_fmac_f32_e32 v74, v76, v74
	v_div_scale_f32 v76, vcc, v67, v69, v67
	v_mul_f32_e32 v77, v76, v74
	v_fma_f32 v78, -v72, v77, v76
	v_fmac_f32_e32 v77, v78, v74
	v_fma_f32 v72, -v72, v77, v76
	v_div_fmas_f32 v72, v72, v74, v77
	v_div_fixup_f32 v67, v72, v69, v67
	v_mul_f32_e32 v57, v57, v67
	v_lshlrev_b32_e32 v67, 16, v73
	v_mul_f32_e32 v58, v58, v67
	v_lshlrev_b32_e32 v67, 16, v75
	v_mul_f32_e32 v69, 0xbfb8aa3b, v67
	v_exp_f32_e32 v69, v69
	v_cvt_pk_bf16_f32 v56, v56, v57
	s_nop 0
	v_add_f32_e32 v69, 1.0, v69
	v_div_scale_f32 v72, s[6:7], v69, v69, v67
	v_rcp_f32_e32 v74, v72
	s_nop 0
	v_fma_f32 v76, -v72, v74, 1.0
	v_fmac_f32_e32 v74, v76, v74
	v_div_scale_f32 v76, vcc, v67, v69, v67
	v_mul_f32_e32 v77, v76, v74
	v_fma_f32 v78, -v72, v77, v76
	v_fmac_f32_e32 v77, v78, v74
	v_fma_f32 v72, -v72, v77, v76
	v_div_fmas_f32 v72, v72, v74, v77
	v_div_fixup_f32 v67, v72, v69, v67
	v_mul_f32_e32 v58, v58, v67
	v_and_b32_e32 v67, 0xffff0000, v73
	v_mul_f32_e32 v59, v59, v67
	v_and_b32_e32 v67, 0xffff0000, v75
	v_mul_f32_e32 v69, 0xbfb8aa3b, v67
	v_exp_f32_e32 v69, v69
	s_nop 0
	v_add_f32_e32 v69, 1.0, v69
	v_div_scale_f32 v72, s[6:7], v69, v69, v67
	v_rcp_f32_e32 v73, v72
	s_nop 0
	v_fma_f32 v74, -v72, v73, 1.0
	v_fmac_f32_e32 v73, v74, v73
	v_div_scale_f32 v74, vcc, v67, v69, v67
	v_mul_f32_e32 v75, v74, v73
	v_fma_f32 v76, -v72, v75, v74
	v_fmac_f32_e32 v75, v76, v73
	v_fma_f32 v72, -v72, v75, v74
	v_div_fmas_f32 v72, v72, v73, v75
	v_div_fixup_f32 v67, v72, v69, v67
	v_mul_f32_e32 v59, v59, v67
	v_cvt_pk_bf16_f32 v57, v58, v59
	v_lshl_add_u64 v[58:59], v[62:63], 0, v[2:3]
	global_store_dwordx2 v[58:59], v[56:57], off
	s_nop 0
	s_waitcnt vmcnt(14)
; __device__ __forceinline__ unsigned cvt_pk_bf16(float lo, float hi) { unsigned r; asm("v_cvt_pk_bf16_f32 %0, %1, %2" : "=v"(r) : "v"(lo), "v"(hi)); return r; }
; __device__ __forceinline__ float bflo(unsigned w) { return __uint_as_float(w << 16); }
; __device__ __forceinline__ float bfhi(unsigned w) { return __uint_as_float(w & 0xffff0000u); }
; __device__ __forceinline__ float silu(float x) { return x / (1.f + __expf(-x)); }
; __device__ __forceinline__ void gmlp_item(const Params& p, int l, int mc, int g, LAS unsigned char* lds) {
;     ...
;     const float* bsp = p.b_s + (size_t)(l * 4 + g) * 128;
; #pragma unroll
;     for (int tt = 0; tt < 8; ++tt) {
;         if (tt < ntt) {
;             const int tok = tok0 + tt * 16 + fr; const float bs = bsp[tt * 16 + fr];
; #pragma unroll
;             for (int ct = 0; ct < 2; ++ct) {
;                 const int cb = g * 256 + w * 32 + ct * 16 + fq * 4;
;                 const u32x2 uu = *(const u32x2*)((const u16*)(ws + WS_ZU) + (size_t)tok * 1024 + cb);
;                 const u32x2 gg = *(const u32x2*)((const u16*)(ws + WS_ZGB) + (size_t)tok * 1024 + cb);
;                 const float o0 = bflo(uu.x) * (acc[ct][tt][0] + bs) * silu(bflo(gg.x));
;                 const float o1 = bfhi(uu.x) * (acc[ct][tt][1] + bs) * silu(bfhi(gg.x));
;                 const float o2 = bflo(uu.y) * (acc[ct][tt][2] + bs) * silu(bflo(gg.y));
;                 const float o3 = bfhi(uu.y) * (acc[ct][tt][3] + bs) * silu(bfhi(gg.y));
;                 u32x2 wv; wv.x = cvt_pk_bf16(o0, o1); wv.y = cvt_pk_bf16(o2, o3);
;                 *(u32x2*)((u16*)(ws + WS_OBUF) + (size_t)tok * 2048 + 1024 + cb) = wv;
;             }
;         }
;     }
	v_mov_b32_e32 v56, v188
	v_mov_b32_e32 v57, v189
	v_lshlrev_b32_e32 v64, 16, v56
	v_mul_f32_e32 v52, v52, v64
	s_waitcnt vmcnt(13)
	v_mov_b32_e32 v58, v214
	v_mov_b32_e32 v59, v215
	v_lshlrev_b32_e32 v64, 16, v58
	v_mul_f32_e32 v65, 0xbfb8aa3b, v64
	v_exp_f32_e32 v65, v65
	v_and_b32_e32 v56, 0xffff0000, v56
	v_mul_f32_e32 v53, v53, v56
	v_and_b32_e32 v56, 0xffff0000, v58
	v_add_f32_e32 v65, 1.0, v65
	v_div_scale_f32 v67, s[6:7], v65, v65, v64
	v_rcp_f32_e32 v69, v67
	v_mul_f32_e32 v58, 0xbfb8aa3b, v56
	v_exp_f32_e32 v58, v58
	v_fma_f32 v70, -v67, v69, 1.0
	v_fmac_f32_e32 v69, v70, v69
	v_div_scale_f32 v70, vcc, v64, v65, v64
	v_mul_f32_e32 v71, v70, v69
	v_fma_f32 v72, -v67, v71, v70
	v_fmac_f32_e32 v71, v72, v69
	v_fma_f32 v67, -v67, v71, v70
	v_div_fmas_f32 v67, v67, v69, v71
	v_div_fixup_f32 v64, v67, v65, v64
	v_add_f32_e32 v58, 1.0, v58
	v_mul_f32_e32 v52, v52, v64
	v_div_scale_f32 v64, s[6:7], v58, v58, v56
	v_rcp_f32_e32 v65, v64
	s_nop 0
	v_fma_f32 v67, -v64, v65, 1.0
	v_fmac_f32_e32 v65, v67, v65
	v_div_scale_f32 v67, vcc, v56, v58, v56
	v_mul_f32_e32 v69, v67, v65
	v_fma_f32 v70, -v64, v69, v67
	v_fmac_f32_e32 v69, v70, v65
	v_fma_f32 v64, -v64, v69, v67
	v_div_fmas_f32 v64, v64, v65, v69
	v_div_fixup_f32 v56, v64, v58, v56
	v_mul_f32_e32 v53, v53, v56
	v_lshlrev_b32_e32 v56, 16, v57
	v_mul_f32_e32 v54, v54, v56
	v_lshlrev_b32_e32 v56, 16, v59
	v_mul_f32_e32 v58, 0xbfb8aa3b, v56
	v_exp_f32_e32 v58, v58
	v_cvt_pk_bf16_f32 v52, v52, v53
	s_nop 0
	v_add_f32_e32 v58, 1.0, v58
	v_div_scale_f32 v64, s[6:7], v58, v58, v56
	v_rcp_f32_e32 v65, v64
	s_nop 0
	v_fma_f32 v67, -v64, v65, 1.0
	v_fmac_f32_e32 v65, v67, v65
	v_div_scale_f32 v67, vcc, v56, v58, v56
	v_mul_f32_e32 v69, v67, v65
	v_fma_f32 v70, -v64, v69, v67
	v_fmac_f32_e32 v69, v70, v65
	v_fma_f32 v64, -v64, v69, v67
	v_div_fmas_f32 v64, v64, v65, v69
	v_div_fixup_f32 v56, v64, v58, v56
	v_mul_f32_e32 v54, v54, v56
	v_and_b32_e32 v56, 0xffff0000, v57
	v_mul_f32_e32 v55, v55, v56
	v_and_b32_e32 v56, 0xffff0000, v59
	v_mul_f32_e32 v57, 0xbfb8aa3b, v56
	v_exp_f32_e32 v57, v57
	s_nop 0
	v_add_f32_e32 v57, 1.0, v57
	v_div_scale_f32 v58, s[6:7], v57, v57, v56
	v_rcp_f32_e32 v59, v58
	s_nop 0
	v_fma_f32 v64, -v58, v59, 1.0
	v_fmac_f32_e32 v59, v64, v59
	v_div_scale_f32 v64, vcc, v56, v57, v56
	v_mul_f32_e32 v65, v64, v59
	v_fma_f32 v66, -v58, v65, v64
	v_fmac_f32_e32 v65, v66, v59
	v_fma_f32 v58, -v58, v65, v64
	v_div_fmas_f32 v58, v58, v59, v65
	v_div_fixup_f32 v56, v58, v57, v56
	v_mul_f32_e32 v55, v55, v56
	v_cvt_pk_bf16_f32 v53, v54, v55
	v_lshl_add_u64 v[54:55], v[62:63], 0, v[60:61]
	global_store_dwordx2 v[54:55], v[52:53], off
	v_or_b32_e32 v52, 32, v0
	v_mov_b32_e32 v53, v1
	v_lshlrev_b64 v[54:55], 11, v[52:53]
	v_lshl_add_u64 v[58:59], s[86:87], 0, v[54:55]
	v_lshl_add_u64 v[54:55], s[34:35], 0, v[54:55]
	v_lshl_add_u64 v[58:59], v[58:59], 0, v[2:3]
	v_lshl_add_u64 v[54:55], v[54:55], 0, v[2:3]
	v_lshlrev_b64 v[52:53], 12, v[52:53]
	v_lshl_add_u64 v[52:53], s[58:59], 0, v[52:53]
	v_lshl_add_u64 v[52:53], v[52:53], 0, s[10:11]
	s_waitcnt vmcnt(13)
	v_mov_b32_e32 v56, v180
	v_add_f32_e32 v48, v48, v56
	s_waitcnt vmcnt(12)
	v_mov_b32_e32 v62, v190
	v_mov_b32_e32 v63, v191
	v_lshlrev_b32_e32 v57, 16, v62
	v_mul_f32_e32 v48, v48, v57
	s_waitcnt vmcnt(11)
	v_mov_b32_e32 v64, v216
	v_mov_b32_e32 v65, v217
	v_lshlrev_b32_e32 v57, 16, v64
	v_mul_f32_e32 v66, 0xbfb8aa3b, v57
	v_exp_f32_e32 v66, v66
	v_add_f32_e32 v49, v49, v56
	v_add_f32_e32 v50, v50, v56
	v_add_f32_e32 v51, v51, v56
	v_add_f32_e32 v66, 1.0, v66
	v_div_scale_f32 v67, s[6:7], v66, v66, v57
	v_rcp_f32_e32 v69, v67
	v_add_f32_e32 v44, v44, v56
	v_add_f32_e32 v45, v45, v56
	v_add_f32_e32 v46, v46, v56
	v_fma_f32 v70, -v67, v69, 1.0
	v_fmac_f32_e32 v69, v70, v69
	v_div_scale_f32 v70, vcc, v57, v66, v57
	v_mul_f32_e32 v71, v70, v69
	v_fma_f32 v72, -v67, v71, v70
	v_fmac_f32_e32 v71, v72, v69
	v_fma_f32 v67, -v67, v71, v70
	v_div_fmas_f32 v67, v67, v69, v71
	v_div_fixup_f32 v57, v67, v66, v57
	v_mul_f32_e32 v48, v48, v57
	v_and_b32_e32 v57, 0xffff0000, v62
	v_mul_f32_e32 v49, v49, v57
	v_and_b32_e32 v57, 0xffff0000, v64
	v_mul_f32_e32 v62, 0xbfb8aa3b, v57
	v_exp_f32_e32 v62, v62
	v_add_f32_e32 v47, v47, v56
	v_add_f32_e32 v62, 1.0, v62
	v_div_scale_f32 v64, s[6:7], v62, v62, v57
	v_rcp_f32_e32 v66, v64
	s_nop 0
	v_fma_f32 v67, -v64, v66, 1.0
	v_fmac_f32_e32 v66, v67, v66
	v_div_scale_f32 v67, vcc, v57, v62, v57
	v_mul_f32_e32 v69, v67, v66
	v_fma_f32 v70, -v64, v69, v67
	v_fmac_f32_e32 v69, v70, v66
	v_fma_f32 v64, -v64, v69, v67
	v_div_fmas_f32 v64, v64, v66, v69
	v_div_fixup_f32 v57, v64, v62, v57
	v_mul_f32_e32 v49, v49, v57
	v_lshlrev_b32_e32 v57, 16, v63
	v_mul_f32_e32 v50, v50, v57
	v_lshlrev_b32_e32 v57, 16, v65
	v_mul_f32_e32 v62, 0xbfb8aa3b, v57
	v_exp_f32_e32 v62, v62
	v_cvt_pk_bf16_f32 v48, v48, v49
	s_nop 0
	v_add_f32_e32 v62, 1.0, v62
	v_div_scale_f32 v64, s[6:7], v62, v62, v57
	v_rcp_f32_e32 v66, v64
	s_nop 0
	v_fma_f32 v67, -v64, v66, 1.0
	v_fmac_f32_e32 v66, v67, v66
	v_div_scale_f32 v67, vcc, v57, v62, v57
	v_mul_f32_e32 v69, v67, v66
	v_fma_f32 v70, -v64, v69, v67
	v_fmac_f32_e32 v69, v70, v66
	v_fma_f32 v64, -v64, v69, v67
	v_div_fmas_f32 v64, v64, v66, v69
	v_div_fixup_f32 v57, v64, v62, v57
	v_mul_f32_e32 v50, v50, v57
	v_and_b32_e32 v57, 0xffff0000, v63
	v_mul_f32_e32 v51, v51, v57
	v_and_b32_e32 v57, 0xffff0000, v65
	v_mul_f32_e32 v62, 0xbfb8aa3b, v57
	v_exp_f32_e32 v62, v62
	s_nop 0
	v_add_f32_e32 v62, 1.0, v62
	v_div_scale_f32 v63, s[6:7], v62, v62, v57
	v_rcp_f32_e32 v64, v63
	s_nop 0
	v_fma_f32 v65, -v63, v64, 1.0
	v_fmac_f32_e32 v64, v65, v64
	v_div_scale_f32 v65, vcc, v57, v62, v57
	v_mul_f32_e32 v66, v65, v64
	v_fma_f32 v67, -v63, v66, v65
	v_fmac_f32_e32 v66, v67, v64
	v_fma_f32 v63, -v63, v66, v65
	v_div_fmas_f32 v63, v63, v64, v66
	v_div_fixup_f32 v57, v63, v62, v57
	v_mul_f32_e32 v51, v51, v57
	v_cvt_pk_bf16_f32 v49, v50, v51
	v_lshl_add_u64 v[50:51], v[52:53], 0, v[2:3]
	global_store_dwordx2 v[50:51], v[48:49], off
	s_nop 0
	s_waitcnt vmcnt(11)
; __device__ __forceinline__ unsigned cvt_pk_bf16(float lo, float hi) { unsigned r; asm("v_cvt_pk_bf16_f32 %0, %1, %2" : "=v"(r) : "v"(lo), "v"(hi)); return r; }
; __device__ __forceinline__ float bflo(unsigned w) { return __uint_as_float(w << 16); }
; __device__ __forceinline__ float bfhi(unsigned w) { return __uint_as_float(w & 0xffff0000u); }
; __device__ __forceinline__ float silu(float x) { return x / (1.f + __expf(-x)); }
; __device__ __forceinline__ void gmlp_item(const Params& p, int l, int mc, int g, LAS unsigned char* lds) {
;     ...
;     const float* bsp = p.b_s + (size_t)(l * 4 + g) * 128;
; #pragma unroll
;     for (int tt = 0; tt < 8; ++tt) {
;         if (tt < ntt) {
;             const int tok = tok0 + tt * 16 + fr; const float bs = bsp[tt * 16 + fr];
; #pragma unroll
;             for (int ct = 0; ct < 2; ++ct) {
;                 const int cb = g * 256 + w * 32 + ct * 16 + fq * 4;
;                 const u32x2 uu = *(const u32x2*)((const u16*)(ws + WS_ZU) + (size_t)tok * 1024 + cb);
;                 const u32x2 gg = *(const u32x2*)((const u16*)(ws + WS_ZGB) + (size_t)tok * 1024 + cb);
;                 const float o0 = bflo(uu.x) * (acc[ct][tt][0] + bs) * silu(bflo(gg.x));
;                 const float o1 = bfhi(uu.x) * (acc[ct][tt][1] + bs) * silu(bfhi(gg.x));
;                 const float o2 = bflo(uu.y) * (acc[ct][tt][2] + bs) * silu(bflo(gg.y));
;                 const float o3 = bfhi(uu.y) * (acc[ct][tt][3] + bs) * silu(bfhi(gg.y));
;                 u32x2 wv; wv.x = cvt_pk_bf16(o0, o1); wv.y = cvt_pk_bf16(o2, o3);
;                 *(u32x2*)((u16*)(ws + WS_OBUF) + (size_t)tok * 2048 + 1024 + cb) = wv;
;             }
;         }
;     }
	v_mov_b32_e32 v48, v192
	v_mov_b32_e32 v49, v193
	v_lshlrev_b32_e32 v54, 16, v48
	v_mul_f32_e32 v44, v44, v54
	s_waitcnt vmcnt(10)
	v_mov_b32_e32 v50, v218
	v_mov_b32_e32 v51, v219
	v_lshlrev_b32_e32 v54, 16, v50
	v_mul_f32_e32 v55, 0xbfb8aa3b, v54
	v_exp_f32_e32 v55, v55
	v_and_b32_e32 v48, 0xffff0000, v48
	v_mul_f32_e32 v45, v45, v48
	v_and_b32_e32 v48, 0xffff0000, v50
	v_add_f32_e32 v55, 1.0, v55
	v_div_scale_f32 v57, s[6:7], v55, v55, v54
	v_rcp_f32_e32 v58, v57
	v_mul_f32_e32 v50, 0xbfb8aa3b, v48
	v_exp_f32_e32 v50, v50
	v_fma_f32 v59, -v57, v58, 1.0
	v_fmac_f32_e32 v58, v59, v58
	v_div_scale_f32 v59, vcc, v54, v55, v54
	v_mul_f32_e32 v62, v59, v58
	v_fma_f32 v63, -v57, v62, v59
	v_fmac_f32_e32 v62, v63, v58
	v_fma_f32 v57, -v57, v62, v59
	v_div_fmas_f32 v57, v57, v58, v62
	v_div_fixup_f32 v54, v57, v55, v54
	v_add_f32_e32 v50, 1.0, v50
	v_mul_f32_e32 v44, v44, v54
	v_div_scale_f32 v54, s[6:7], v50, v50, v48
	v_rcp_f32_e32 v55, v54
	s_nop 0
	v_fma_f32 v57, -v54, v55, 1.0
	v_fmac_f32_e32 v55, v57, v55
	v_div_scale_f32 v57, vcc, v48, v50, v48
	v_mul_f32_e32 v58, v57, v55
	v_fma_f32 v59, -v54, v58, v57
	v_fmac_f32_e32 v58, v59, v55
	v_fma_f32 v54, -v54, v58, v57
	v_div_fmas_f32 v54, v54, v55, v58
	v_div_fixup_f32 v48, v54, v50, v48
	v_mul_f32_e32 v45, v45, v48
	v_lshlrev_b32_e32 v48, 16, v49
	v_mul_f32_e32 v46, v46, v48
	v_lshlrev_b32_e32 v48, 16, v51
	v_mul_f32_e32 v50, 0xbfb8aa3b, v48
	v_exp_f32_e32 v50, v50
	v_cvt_pk_bf16_f32 v44, v44, v45
	s_nop 0
	v_add_f32_e32 v50, 1.0, v50
	v_div_scale_f32 v54, s[6:7], v50, v50, v48
	v_rcp_f32_e32 v55, v54
	s_nop 0
	v_fma_f32 v57, -v54, v55, 1.0
	v_fmac_f32_e32 v55, v57, v55
	v_div_scale_f32 v57, vcc, v48, v50, v48
	v_mul_f32_e32 v58, v57, v55
	v_fma_f32 v59, -v54, v58, v57
	v_fmac_f32_e32 v58, v59, v55
	v_fma_f32 v54, -v54, v58, v57
	v_div_fmas_f32 v54, v54, v55, v58
	v_div_fixup_f32 v48, v54, v50, v48
	v_mul_f32_e32 v46, v46, v48
	v_and_b32_e32 v48, 0xffff0000, v49
	v_mul_f32_e32 v47, v47, v48
	v_and_b32_e32 v48, 0xffff0000, v51
	v_mul_f32_e32 v49, 0xbfb8aa3b, v48
	v_exp_f32_e32 v49, v49
	s_nop 0
	v_add_f32_e32 v49, 1.0, v49
	v_div_scale_f32 v50, s[6:7], v49, v49, v48
	v_rcp_f32_e32 v51, v50
	s_nop 0
	v_fma_f32 v54, -v50, v51, 1.0
	v_fmac_f32_e32 v51, v54, v51
	v_div_scale_f32 v54, vcc, v48, v49, v48
	v_mul_f32_e32 v55, v54, v51
	v_fma_f32 v56, -v50, v55, v54
	v_fmac_f32_e32 v55, v56, v51
	v_fma_f32 v50, -v50, v55, v54
	v_div_fmas_f32 v50, v50, v51, v55
	v_div_fixup_f32 v48, v50, v49, v48
	v_mul_f32_e32 v47, v47, v48
	v_cvt_pk_bf16_f32 v45, v46, v47
	v_lshl_add_u64 v[46:47], v[52:53], 0, v[60:61]
	global_store_dwordx2 v[46:47], v[44:45], off
	v_or_b32_e32 v44, 48, v0
	v_mov_b32_e32 v45, v1
	v_lshlrev_b64 v[46:47], 11, v[44:45]
	v_lshl_add_u64 v[50:51], s[86:87], 0, v[46:47]
	v_lshl_add_u64 v[46:47], s[34:35], 0, v[46:47]
	v_lshl_add_u64 v[50:51], v[50:51], 0, v[2:3]
	v_lshl_add_u64 v[46:47], v[46:47], 0, v[2:3]
	v_lshlrev_b64 v[44:45], 12, v[44:45]
	v_lshl_add_u64 v[44:45], s[58:59], 0, v[44:45]
	v_lshl_add_u64 v[44:45], v[44:45], 0, s[10:11]
	s_waitcnt vmcnt(10)
	v_mov_b32_e32 v48, v181
	v_add_f32_e32 v40, v40, v48
	s_waitcnt vmcnt(9)
	v_mov_b32_e32 v52, v194
	v_mov_b32_e32 v53, v195
	v_lshlrev_b32_e32 v49, 16, v52
	v_mul_f32_e32 v40, v40, v49
	s_waitcnt vmcnt(8)
	v_mov_b32_e32 v54, v220
	v_mov_b32_e32 v55, v221
	v_lshlrev_b32_e32 v49, 16, v54
	v_mul_f32_e32 v56, 0xbfb8aa3b, v49
	v_exp_f32_e32 v56, v56
	v_add_f32_e32 v41, v41, v48
	v_add_f32_e32 v42, v42, v48
	v_add_f32_e32 v43, v43, v48
	v_add_f32_e32 v56, 1.0, v56
	v_div_scale_f32 v57, s[6:7], v56, v56, v49
	v_rcp_f32_e32 v58, v57
	v_add_f32_e32 v36, v36, v48
	v_add_f32_e32 v37, v37, v48
	v_add_f32_e32 v38, v38, v48
	v_fma_f32 v59, -v57, v58, 1.0
	v_fmac_f32_e32 v58, v59, v58
	v_div_scale_f32 v59, vcc, v49, v56, v49
	v_mul_f32_e32 v62, v59, v58
	v_fma_f32 v63, -v57, v62, v59
	v_fmac_f32_e32 v62, v63, v58
	v_fma_f32 v57, -v57, v62, v59
	v_div_fmas_f32 v57, v57, v58, v62
	v_div_fixup_f32 v49, v57, v56, v49
	v_mul_f32_e32 v40, v40, v49
	v_and_b32_e32 v49, 0xffff0000, v52
	v_mul_f32_e32 v41, v41, v49
	v_and_b32_e32 v49, 0xffff0000, v54
	v_mul_f32_e32 v52, 0xbfb8aa3b, v49
	v_exp_f32_e32 v52, v52
	v_add_f32_e32 v39, v39, v48
	v_add_f32_e32 v52, 1.0, v52
	v_div_scale_f32 v54, s[6:7], v52, v52, v49
	v_rcp_f32_e32 v56, v54
	s_nop 0
	v_fma_f32 v57, -v54, v56, 1.0
	v_fmac_f32_e32 v56, v57, v56
	v_div_scale_f32 v57, vcc, v49, v52, v49
	v_mul_f32_e32 v58, v57, v56
	v_fma_f32 v59, -v54, v58, v57
	v_fmac_f32_e32 v58, v59, v56
	v_fma_f32 v54, -v54, v58, v57
	v_div_fmas_f32 v54, v54, v56, v58
	v_div_fixup_f32 v49, v54, v52, v49
	v_mul_f32_e32 v41, v41, v49
	v_lshlrev_b32_e32 v49, 16, v53
	v_mul_f32_e32 v42, v42, v49
	v_lshlrev_b32_e32 v49, 16, v55
	v_mul_f32_e32 v52, 0xbfb8aa3b, v49
	v_exp_f32_e32 v52, v52
	v_cvt_pk_bf16_f32 v40, v40, v41
	s_nop 0
	v_add_f32_e32 v52, 1.0, v52
	v_div_scale_f32 v54, s[6:7], v52, v52, v49
	v_rcp_f32_e32 v56, v54
	s_nop 0
	v_fma_f32 v57, -v54, v56, 1.0
	v_fmac_f32_e32 v56, v57, v56
	v_div_scale_f32 v57, vcc, v49, v52, v49
	v_mul_f32_e32 v58, v57, v56
	v_fma_f32 v59, -v54, v58, v57
	v_fmac_f32_e32 v58, v59, v56
	v_fma_f32 v54, -v54, v58, v57
	v_div_fmas_f32 v54, v54, v56, v58
	v_div_fixup_f32 v49, v54, v52, v49
	v_mul_f32_e32 v42, v42, v49
	v_and_b32_e32 v49, 0xffff0000, v53
	v_mul_f32_e32 v43, v43, v49
	v_and_b32_e32 v49, 0xffff0000, v55
	v_mul_f32_e32 v52, 0xbfb8aa3b, v49
	v_exp_f32_e32 v52, v52
	s_nop 0
	v_add_f32_e32 v52, 1.0, v52
	v_div_scale_f32 v53, s[6:7], v52, v52, v49
	v_rcp_f32_e32 v54, v53
	s_nop 0
	v_fma_f32 v55, -v53, v54, 1.0
	v_fmac_f32_e32 v54, v55, v54
	v_div_scale_f32 v55, vcc, v49, v52, v49
	v_mul_f32_e32 v56, v55, v54
	v_fma_f32 v57, -v53, v56, v55
	v_fmac_f32_e32 v56, v57, v54
	v_fma_f32 v53, -v53, v56, v55
	v_div_fmas_f32 v53, v53, v54, v56
	v_div_fixup_f32 v49, v53, v52, v49
	v_mul_f32_e32 v43, v43, v49
	v_cvt_pk_bf16_f32 v41, v42, v43
	v_lshl_add_u64 v[42:43], v[44:45], 0, v[2:3]
	global_store_dwordx2 v[42:43], v[40:41], off
	s_nop 0
	s_waitcnt vmcnt(8)
; __device__ __forceinline__ unsigned cvt_pk_bf16(float lo, float hi) { unsigned r; asm("v_cvt_pk_bf16_f32 %0, %1, %2" : "=v"(r) : "v"(lo), "v"(hi)); return r; }
; __device__ __forceinline__ float bflo(unsigned w) { return __uint_as_float(w << 16); }
; __device__ __forceinline__ float bfhi(unsigned w) { return __uint_as_float(w & 0xffff0000u); }
; __device__ __forceinline__ float silu(float x) { return x / (1.f + __expf(-x)); }
; __device__ __forceinline__ void gmlp_item(const Params& p, int l, int mc, int g, LAS unsigned char* lds) {
;     ...
;     const float* bsp = p.b_s + (size_t)(l * 4 + g) * 128;
; #pragma unroll
;     for (int tt = 0; tt < 8; ++tt) {
;         if (tt < ntt) {
;             const int tok = tok0 + tt * 16 + fr; const float bs = bsp[tt * 16 + fr];
; #pragma unroll
;             for (int ct = 0; ct < 2; ++ct) {
;                 const int cb = g * 256 + w * 32 + ct * 16 + fq * 4;
;                 const u32x2 uu = *(const u32x2*)((const u16*)(ws + WS_ZU) + (size_t)tok * 1024 + cb);
;                 const u32x2 gg = *(const u32x2*)((const u16*)(ws + WS_ZGB) + (size_t)tok * 1024 + cb);
;                 const float o0 = bflo(uu.x) * (acc[ct][tt][0] + bs) * silu(bflo(gg.x));
;                 const float o1 = bfhi(uu.x) * (acc[ct][tt][1] + bs) * silu(bfhi(gg.x));
;                 const float o2 = bflo(uu.y) * (acc[ct][tt][2] + bs) * silu(bflo(gg.y));
;                 const float o3 = bfhi(uu.y) * (acc[ct][tt][3] + bs) * silu(bfhi(gg.y));
;                 u32x2 wv; wv.x = cvt_pk_bf16(o0, o1); wv.y = cvt_pk_bf16(o2, o3);
;                 *(u32x2*)((u16*)(ws + WS_OBUF) + (size_t)tok * 2048 + 1024 + cb) = wv;
;             }
;         }
;     }
	v_mov_b32_e32 v40, v196
	v_mov_b32_e32 v41, v197
	v_lshlrev_b32_e32 v46, 16, v40
	v_mul_f32_e32 v36, v36, v46
	s_waitcnt vmcnt(7)
	v_mov_b32_e32 v42, v222
	v_mov_b32_e32 v43, v223
	v_lshlrev_b32_e32 v46, 16, v42
	v_mul_f32_e32 v47, 0xbfb8aa3b, v46
	v_exp_f32_e32 v47, v47
	v_and_b32_e32 v40, 0xffff0000, v40
	v_mul_f32_e32 v37, v37, v40
	v_and_b32_e32 v40, 0xffff0000, v42
	v_add_f32_e32 v47, 1.0, v47
	v_div_scale_f32 v49, s[6:7], v47, v47, v46
	v_rcp_f32_e32 v50, v49
	v_mul_f32_e32 v42, 0xbfb8aa3b, v40
	v_exp_f32_e32 v42, v42
	v_fma_f32 v51, -v49, v50, 1.0
	v_fmac_f32_e32 v50, v51, v50
	v_div_scale_f32 v51, vcc, v46, v47, v46
	v_mul_f32_e32 v52, v51, v50
	v_fma_f32 v53, -v49, v52, v51
	v_fmac_f32_e32 v52, v53, v50
	v_fma_f32 v49, -v49, v52, v51
	v_div_fmas_f32 v49, v49, v50, v52
	v_div_fixup_f32 v46, v49, v47, v46
	v_add_f32_e32 v42, 1.0, v42
	v_mul_f32_e32 v36, v36, v46
	v_div_scale_f32 v46, s[6:7], v42, v42, v40
	v_rcp_f32_e32 v47, v46
	s_nop 0
	v_fma_f32 v49, -v46, v47, 1.0
	v_fmac_f32_e32 v47, v49, v47
	v_div_scale_f32 v49, vcc, v40, v42, v40
	v_mul_f32_e32 v50, v49, v47
	v_fma_f32 v51, -v46, v50, v49
	v_fmac_f32_e32 v50, v51, v47
	v_fma_f32 v46, -v46, v50, v49
	v_div_fmas_f32 v46, v46, v47, v50
	v_div_fixup_f32 v40, v46, v42, v40
	v_mul_f32_e32 v37, v37, v40
	v_lshlrev_b32_e32 v40, 16, v41
	v_mul_f32_e32 v38, v38, v40
	v_lshlrev_b32_e32 v40, 16, v43
	v_mul_f32_e32 v42, 0xbfb8aa3b, v40
	v_exp_f32_e32 v42, v42
	v_cvt_pk_bf16_f32 v36, v36, v37
	s_nop 0
	v_add_f32_e32 v42, 1.0, v42
	v_div_scale_f32 v46, s[6:7], v42, v42, v40
	v_rcp_f32_e32 v47, v46
	s_nop 0
	v_fma_f32 v49, -v46, v47, 1.0
	v_fmac_f32_e32 v47, v49, v47
	v_div_scale_f32 v49, vcc, v40, v42, v40
	v_mul_f32_e32 v50, v49, v47
	v_fma_f32 v51, -v46, v50, v49
	v_fmac_f32_e32 v50, v51, v47
	v_fma_f32 v46, -v46, v50, v49
	v_div_fmas_f32 v46, v46, v47, v50
	v_div_fixup_f32 v40, v46, v42, v40
	v_mul_f32_e32 v38, v38, v40
	v_and_b32_e32 v40, 0xffff0000, v41
	v_mul_f32_e32 v39, v39, v40
	v_and_b32_e32 v40, 0xffff0000, v43
	v_mul_f32_e32 v41, 0xbfb8aa3b, v40
	v_exp_f32_e32 v41, v41
	s_nop 0
	v_add_f32_e32 v41, 1.0, v41
	v_div_scale_f32 v42, s[6:7], v41, v41, v40
	v_rcp_f32_e32 v43, v42
	s_nop 0
	v_fma_f32 v46, -v42, v43, 1.0
	v_fmac_f32_e32 v43, v46, v43
	v_div_scale_f32 v46, vcc, v40, v41, v40
	v_mul_f32_e32 v47, v46, v43
	v_fma_f32 v48, -v42, v47, v46
	v_fmac_f32_e32 v47, v48, v43
	v_fma_f32 v42, -v42, v47, v46
	v_div_fmas_f32 v42, v42, v43, v47
	v_div_fixup_f32 v40, v42, v41, v40
	v_mul_f32_e32 v39, v39, v40
	v_cvt_pk_bf16_f32 v37, v38, v39
	v_lshl_add_u64 v[38:39], v[44:45], 0, v[60:61]
	s_and_b64 vcc, exec, s[38:39]
	global_store_dwordx2 v[38:39], v[36:37], off
	s_cbranch_vccnz .LBB0_768
	s_mov_b64 s[98:99], 0x8000
	v_mov_b32_e32 v224, v228
	v_mov_b32_e32 v225, v229
	v_mov_b32_e32 v226, v230
	v_mov_b32_e32 v227, v231
	global_load_dword v178, v[232:233], off
	global_load_dwordx2 v[182:183], v[224:225], off
	global_load_dwordx2 v[208:209], v[226:227], off
	global_load_dwordx2 v[184:185], v[224:225], off offset:32
	global_load_dwordx2 v[210:211], v[226:227], off offset:32
	v_lshl_add_u64 v[224:225], v[224:225], 0, s[98:99]
	v_lshl_add_u64 v[226:227], v[226:227], 0, s[98:99]
	global_load_dword v179, v[232:233], off offset:64
	global_load_dwordx2 v[186:187], v[224:225], off
	global_load_dwordx2 v[212:213], v[226:227], off
	global_load_dwordx2 v[188:189], v[224:225], off offset:32
	global_load_dwordx2 v[214:215], v[226:227], off offset:32
	v_lshl_add_u64 v[224:225], v[224:225], 0, s[98:99]
	v_lshl_add_u64 v[226:227], v[226:227], 0, s[98:99]
	global_load_dword v180, v[232:233], off offset:128
	global_load_dwordx2 v[190:191], v[224:225], off
	global_load_dwordx2 v[216:217], v[226:227], off
	global_load_dwordx2 v[192:193], v[224:225], off offset:32
	global_load_dwordx2 v[218:219], v[226:227], off offset:32
	v_lshl_add_u64 v[224:225], v[224:225], 0, s[98:99]
	v_lshl_add_u64 v[226:227], v[226:227], 0, s[98:99]
	global_load_dword v181, v[232:233], off offset:192
	global_load_dwordx2 v[194:195], v[224:225], off
	global_load_dwordx2 v[220:221], v[226:227], off
	global_load_dwordx2 v[196:197], v[224:225], off offset:32
	global_load_dwordx2 v[222:223], v[226:227], off offset:32
	v_lshl_add_u64 v[224:225], v[224:225], 0, s[98:99]
	v_lshl_add_u64 v[226:227], v[226:227], 0, s[98:99]
	v_add_u32_e32 v38, 64, v0
	v_mov_b32_e32 v39, v1
	v_lshlrev_b64 v[40:41], 11, v[38:39]
	v_mov_b32_e32 v69, v1
	v_lshl_add_u64 v[44:45], s[86:87], 0, v[40:41]
	v_lshl_add_u64 v[36:37], s[0:1], 0, v[68:69]
	v_lshl_add_u64 v[40:41], s[34:35], 0, v[40:41]
	v_lshl_add_u64 v[44:45], v[44:45], 0, v[2:3]
	v_lshl_add_u64 v[40:41], v[40:41], 0, v[2:3]
	v_lshlrev_b64 v[38:39], 12, v[38:39]
	v_lshl_add_u64 v[38:39], s[58:59], 0, v[38:39]
	s_mov_b64 s[6:7], 0x2958c800
	v_lshl_add_u64 v[38:39], v[38:39], 0, s[6:7]
	s_waitcnt vmcnt(19)
	v_mov_b32_e32 v42, v178
	v_add_f32_e32 v32, v32, v42
	s_waitcnt vmcnt(18)
	v_mov_b32_e32 v46, v182
	v_mov_b32_e32 v47, v183
	v_lshlrev_b32_e32 v43, 16, v46
	v_mul_f32_e32 v32, v32, v43
	s_waitcnt vmcnt(17)
; __device__ __forceinline__ unsigned cvt_pk_bf16(float lo, float hi) { unsigned r; asm("v_cvt_pk_bf16_f32 %0, %1, %2" : "=v"(r) : "v"(lo), "v"(hi)); return r; }
; __device__ __forceinline__ float bflo(unsigned w) { return __uint_as_float(w << 16); }
; __device__ __forceinline__ float bfhi(unsigned w) { return __uint_as_float(w & 0xffff0000u); }
; __device__ __forceinline__ float silu(float x) { return x / (1.f + __expf(-x)); }
; __device__ __forceinline__ void gmlp_item(const Params& p, int l, int mc, int g, LAS unsigned char* lds) {
;     ...
;     const float* bsp = p.b_s + (size_t)(l * 4 + g) * 128;
; #pragma unroll
;     for (int tt = 0; tt < 8; ++tt) {
;         if (tt < ntt) {
;             const int tok = tok0 + tt * 16 + fr; const float bs = bsp[tt * 16 + fr];
; #pragma unroll
;             for (int ct = 0; ct < 2; ++ct) {
;                 const int cb = g * 256 + w * 32 + ct * 16 + fq * 4;
;                 const u32x2 uu = *(const u32x2*)((const u16*)(ws + WS_ZU) + (size_t)tok * 1024 + cb);
;                 const u32x2 gg = *(const u32x2*)((const u16*)(ws + WS_ZGB) + (size_t)tok * 1024 + cb);
;                 const float o0 = bflo(uu.x) * (acc[ct][tt][0] + bs) * silu(bflo(gg.x));
;                 const float o1 = bfhi(uu.x) * (acc[ct][tt][1] + bs) * silu(bfhi(gg.x));
;                 const float o2 = bflo(uu.y) * (acc[ct][tt][2] + bs) * silu(bflo(gg.y));
;                 const float o3 = bfhi(uu.y) * (acc[ct][tt][3] + bs) * silu(bfhi(gg.y));
;                 u32x2 wv; wv.x = cvt_pk_bf16(o0, o1); wv.y = cvt_pk_bf16(o2, o3);
;                 *(u32x2*)((u16*)(ws + WS_OBUF) + (size_t)tok * 2048 + 1024 + cb) = wv;
;             }
;         }
;     }
	v_mov_b32_e32 v48, v208
	v_mov_b32_e32 v49, v209
	v_lshlrev_b32_e32 v43, 16, v48
	v_mul_f32_e32 v50, 0xbfb8aa3b, v43
	v_exp_f32_e32 v50, v50
	v_add_f32_e32 v33, v33, v42
	v_add_f32_e32 v34, v34, v42
	v_add_f32_e32 v35, v35, v42
	v_add_f32_e32 v50, 1.0, v50
	v_div_scale_f32 v51, s[0:1], v50, v50, v43
	v_rcp_f32_e32 v52, v51
	v_add_f32_e32 v28, v28, v42
	v_add_f32_e32 v29, v29, v42
	v_add_f32_e32 v30, v30, v42
	v_fma_f32 v53, -v51, v52, 1.0
	v_fmac_f32_e32 v52, v53, v52
	v_div_scale_f32 v53, vcc, v43, v50, v43
	v_mul_f32_e32 v54, v53, v52
	v_fma_f32 v55, -v51, v54, v53
	v_fmac_f32_e32 v54, v55, v52
	v_fma_f32 v51, -v51, v54, v53
	v_div_fmas_f32 v51, v51, v52, v54
	v_div_fixup_f32 v43, v51, v50, v43
	v_mul_f32_e32 v32, v32, v43
	v_and_b32_e32 v43, 0xffff0000, v46
	v_mul_f32_e32 v33, v33, v43
	v_and_b32_e32 v43, 0xffff0000, v48
	v_mul_f32_e32 v46, 0xbfb8aa3b, v43
	v_exp_f32_e32 v46, v46
	v_add_f32_e32 v31, v31, v42
	v_add_f32_e32 v46, 1.0, v46
	v_div_scale_f32 v48, s[0:1], v46, v46, v43
	v_rcp_f32_e32 v50, v48
	s_nop 0
	v_fma_f32 v51, -v48, v50, 1.0
	v_fmac_f32_e32 v50, v51, v50
	v_div_scale_f32 v51, vcc, v43, v46, v43
	v_mul_f32_e32 v52, v51, v50
	v_fma_f32 v53, -v48, v52, v51
	v_fmac_f32_e32 v52, v53, v50
	v_fma_f32 v48, -v48, v52, v51
	v_div_fmas_f32 v48, v48, v50, v52
	v_div_fixup_f32 v43, v48, v46, v43
	v_mul_f32_e32 v33, v33, v43
	v_lshlrev_b32_e32 v43, 16, v47
	v_mul_f32_e32 v34, v34, v43
	v_lshlrev_b32_e32 v43, 16, v49
	v_mul_f32_e32 v46, 0xbfb8aa3b, v43
	v_exp_f32_e32 v46, v46
	v_cvt_pk_bf16_f32 v32, v32, v33
	s_nop 0
	v_add_f32_e32 v46, 1.0, v46
	v_div_scale_f32 v48, s[0:1], v46, v46, v43
	v_rcp_f32_e32 v50, v48
	s_nop 0
	v_fma_f32 v51, -v48, v50, 1.0
	v_fmac_f32_e32 v50, v51, v50
	v_div_scale_f32 v51, vcc, v43, v46, v43
	v_mul_f32_e32 v52, v51, v50
	v_fma_f32 v53, -v48, v52, v51
	v_fmac_f32_e32 v52, v53, v50
	v_fma_f32 v48, -v48, v52, v51
	v_div_fmas_f32 v48, v48, v50, v52
	v_div_fixup_f32 v43, v48, v46, v43
	v_mul_f32_e32 v34, v34, v43
	v_and_b32_e32 v43, 0xffff0000, v47
	v_mul_f32_e32 v35, v35, v43
	v_and_b32_e32 v43, 0xffff0000, v49
	v_mul_f32_e32 v46, 0xbfb8aa3b, v43
	v_exp_f32_e32 v46, v46
	s_nop 0
	v_add_f32_e32 v46, 1.0, v46
	v_div_scale_f32 v47, s[0:1], v46, v46, v43
	v_rcp_f32_e32 v48, v47
	s_nop 0
	v_fma_f32 v49, -v47, v48, 1.0
	v_fmac_f32_e32 v48, v49, v48
	v_div_scale_f32 v49, vcc, v43, v46, v43
	v_mul_f32_e32 v50, v49, v48
	v_fma_f32 v51, -v47, v50, v49
	v_fmac_f32_e32 v50, v51, v48
	v_fma_f32 v47, -v47, v50, v49
	v_div_fmas_f32 v47, v47, v48, v50
	v_div_fixup_f32 v43, v47, v46, v43
	v_mul_f32_e32 v35, v35, v43
	v_cvt_pk_bf16_f32 v33, v34, v35
	v_lshl_add_u64 v[34:35], v[38:39], 0, v[2:3]
	global_store_dwordx2 v[34:35], v[32:33], off
	s_nop 0
	s_waitcnt vmcnt(17)
	v_mov_b32_e32 v32, v184
	v_mov_b32_e32 v33, v185
	v_lshlrev_b32_e32 v40, 16, v32
	v_mul_f32_e32 v28, v28, v40
	s_waitcnt vmcnt(16)
	v_mov_b32_e32 v34, v210
	v_mov_b32_e32 v35, v211
	v_lshlrev_b32_e32 v40, 16, v34
	v_mul_f32_e32 v41, 0xbfb8aa3b, v40
	v_exp_f32_e32 v41, v41
	v_and_b32_e32 v32, 0xffff0000, v32
	v_mul_f32_e32 v29, v29, v32
	v_and_b32_e32 v32, 0xffff0000, v34
	v_add_f32_e32 v41, 1.0, v41
	v_div_scale_f32 v43, s[0:1], v41, v41, v40
	v_rcp_f32_e32 v44, v43
	v_mul_f32_e32 v34, 0xbfb8aa3b, v32
	v_exp_f32_e32 v34, v34
	v_fma_f32 v45, -v43, v44, 1.0
	v_fmac_f32_e32 v44, v45, v44
	v_div_scale_f32 v45, vcc, v40, v41, v40
	v_mul_f32_e32 v46, v45, v44
	v_fma_f32 v47, -v43, v46, v45
	v_fmac_f32_e32 v46, v47, v44
	v_fma_f32 v43, -v43, v46, v45
	v_div_fmas_f32 v43, v43, v44, v46
	v_div_fixup_f32 v40, v43, v41, v40
	v_add_f32_e32 v34, 1.0, v34
	v_mul_f32_e32 v28, v28, v40
	v_div_scale_f32 v40, s[0:1], v34, v34, v32
	v_rcp_f32_e32 v41, v40
	s_nop 0
	v_fma_f32 v43, -v40, v41, 1.0
	v_fmac_f32_e32 v41, v43, v41
	v_div_scale_f32 v43, vcc, v32, v34, v32
	v_mul_f32_e32 v44, v43, v41
	v_fma_f32 v45, -v40, v44, v43
	v_fmac_f32_e32 v44, v45, v41
	v_fma_f32 v40, -v40, v44, v43
	v_div_fmas_f32 v40, v40, v41, v44
	v_div_fixup_f32 v32, v40, v34, v32
	v_mul_f32_e32 v29, v29, v32
	v_lshlrev_b32_e32 v32, 16, v33
	v_mul_f32_e32 v30, v30, v32
	v_lshlrev_b32_e32 v32, 16, v35
	v_mul_f32_e32 v34, 0xbfb8aa3b, v32
	v_exp_f32_e32 v34, v34
	v_cvt_pk_bf16_f32 v28, v28, v29
	s_nop 0
	v_add_f32_e32 v34, 1.0, v34
	v_div_scale_f32 v40, s[0:1], v34, v34, v32
	v_rcp_f32_e32 v41, v40
	s_nop 0
	v_fma_f32 v43, -v40, v41, 1.0
	v_fmac_f32_e32 v41, v43, v41
	v_div_scale_f32 v43, vcc, v32, v34, v32
	v_mul_f32_e32 v44, v43, v41
	v_fma_f32 v45, -v40, v44, v43
	v_fmac_f32_e32 v44, v45, v41
	v_fma_f32 v40, -v40, v44, v43
	v_div_fmas_f32 v40, v40, v41, v44
	v_div_fixup_f32 v32, v40, v34, v32
	v_mul_f32_e32 v30, v30, v32
	v_and_b32_e32 v32, 0xffff0000, v33
	v_mul_f32_e32 v31, v31, v32
	v_and_b32_e32 v32, 0xffff0000, v35
	v_mul_f32_e32 v33, 0xbfb8aa3b, v32
	v_exp_f32_e32 v33, v33
	s_nop 0
	v_add_f32_e32 v33, 1.0, v33
	v_div_scale_f32 v34, s[0:1], v33, v33, v32
	v_rcp_f32_e32 v35, v34
	s_nop 0
	v_fma_f32 v40, -v34, v35, 1.0
	v_fmac_f32_e32 v35, v40, v35
	v_div_scale_f32 v40, vcc, v32, v33, v32
	v_mul_f32_e32 v41, v40, v35
	v_fma_f32 v42, -v34, v41, v40
	v_fmac_f32_e32 v41, v42, v35
	v_fma_f32 v34, -v34, v41, v40
	v_div_fmas_f32 v34, v34, v35, v41
	v_div_fixup_f32 v32, v34, v33, v32
	v_mul_f32_e32 v31, v31, v32
	v_cvt_pk_bf16_f32 v29, v30, v31
	v_lshl_add_u64 v[30:31], v[38:39], 0, v[60:61]
	global_store_dwordx2 v[30:31], v[28:29], off
	v_add_u32_e32 v28, 0x50, v0
	v_mov_b32_e32 v29, v1
	v_lshlrev_b64 v[30:31], 11, v[28:29]
	v_lshl_add_u64 v[34:35], s[86:87], 0, v[30:31]
	v_lshl_add_u64 v[30:31], s[34:35], 0, v[30:31]
	v_lshl_add_u64 v[34:35], v[34:35], 0, v[2:3]
	v_lshl_add_u64 v[30:31], v[30:31], 0, v[2:3]
	v_lshlrev_b64 v[28:29], 12, v[28:29]
	v_lshl_add_u64 v[28:29], s[58:59], 0, v[28:29]
	v_lshl_add_u64 v[28:29], v[28:29], 0, s[6:7]
	s_waitcnt vmcnt(16)
; __device__ __forceinline__ unsigned cvt_pk_bf16(float lo, float hi) { unsigned r; asm("v_cvt_pk_bf16_f32 %0, %1, %2" : "=v"(r) : "v"(lo), "v"(hi)); return r; }
; __device__ __forceinline__ float bflo(unsigned w) { return __uint_as_float(w << 16); }
; __device__ __forceinline__ float bfhi(unsigned w) { return __uint_as_float(w & 0xffff0000u); }
; __device__ __forceinline__ float silu(float x) { return x / (1.f + __expf(-x)); }
; __device__ __forceinline__ void gmlp_item(const Params& p, int l, int mc, int g, LAS unsigned char* lds) {
;     ...
;     const float* bsp = p.b_s + (size_t)(l * 4 + g) * 128;
; #pragma unroll
;     for (int tt = 0; tt < 8; ++tt) {
;         if (tt < ntt) {
;             const int tok = tok0 + tt * 16 + fr; const float bs = bsp[tt * 16 + fr];
; #pragma unroll
;             for (int ct = 0; ct < 2; ++ct) {
;                 const int cb = g * 256 + w * 32 + ct * 16 + fq * 4;
;                 const u32x2 uu = *(const u32x2*)((const u16*)(ws + WS_ZU) + (size_t)tok * 1024 + cb);
;                 const u32x2 gg = *(const u32x2*)((const u16*)(ws + WS_ZGB) + (size_t)tok * 1024 + cb);
;                 const float o0 = bflo(uu.x) * (acc[ct][tt][0] + bs) * silu(bflo(gg.x));
;                 const float o1 = bfhi(uu.x) * (acc[ct][tt][1] + bs) * silu(bfhi(gg.x));
;                 const float o2 = bflo(uu.y) * (acc[ct][tt][2] + bs) * silu(bflo(gg.y));
;                 const float o3 = bfhi(uu.y) * (acc[ct][tt][3] + bs) * silu(bfhi(gg.y));
;                 u32x2 wv; wv.x = cvt_pk_bf16(o0, o1); wv.y = cvt_pk_bf16(o2, o3);
;                 *(u32x2*)((u16*)(ws + WS_OBUF) + (size_t)tok * 2048 + 1024 + cb) = wv;
;             }
;         }
;     }
	v_mov_b32_e32 v32, v179
	v_add_f32_e32 v24, v24, v32
	s_waitcnt vmcnt(15)
	v_mov_b32_e32 v38, v186
	v_mov_b32_e32 v39, v187
	v_lshlrev_b32_e32 v33, 16, v38
	v_mul_f32_e32 v24, v24, v33
	s_waitcnt vmcnt(14)
	v_mov_b32_e32 v40, v212
	v_mov_b32_e32 v41, v213
	v_lshlrev_b32_e32 v33, 16, v40
	v_mul_f32_e32 v42, 0xbfb8aa3b, v33
	v_exp_f32_e32 v42, v42
	v_add_f32_e32 v25, v25, v32
	v_add_f32_e32 v26, v26, v32
	v_add_f32_e32 v27, v27, v32
	v_add_f32_e32 v42, 1.0, v42
	v_div_scale_f32 v43, s[0:1], v42, v42, v33
	v_rcp_f32_e32 v44, v43
	v_add_f32_e32 v20, v20, v32
	v_add_f32_e32 v21, v21, v32
	v_add_f32_e32 v22, v22, v32
	v_fma_f32 v45, -v43, v44, 1.0
	v_fmac_f32_e32 v44, v45, v44
	v_div_scale_f32 v45, vcc, v33, v42, v33
	v_mul_f32_e32 v46, v45, v44
	v_fma_f32 v47, -v43, v46, v45
	v_fmac_f32_e32 v46, v47, v44
	v_fma_f32 v43, -v43, v46, v45
	v_div_fmas_f32 v43, v43, v44, v46
	v_div_fixup_f32 v33, v43, v42, v33
	v_mul_f32_e32 v24, v24, v33
	v_and_b32_e32 v33, 0xffff0000, v38
	v_mul_f32_e32 v25, v25, v33
	v_and_b32_e32 v33, 0xffff0000, v40
	v_mul_f32_e32 v38, 0xbfb8aa3b, v33
	v_exp_f32_e32 v38, v38
	v_add_f32_e32 v23, v23, v32
	v_add_f32_e32 v38, 1.0, v38
	v_div_scale_f32 v40, s[0:1], v38, v38, v33
	v_rcp_f32_e32 v42, v40
	s_nop 0
	v_fma_f32 v43, -v40, v42, 1.0
	v_fmac_f32_e32 v42, v43, v42
	v_div_scale_f32 v43, vcc, v33, v38, v33
	v_mul_f32_e32 v44, v43, v42
	v_fma_f32 v45, -v40, v44, v43
	v_fmac_f32_e32 v44, v45, v42
	v_fma_f32 v40, -v40, v44, v43
	v_div_fmas_f32 v40, v40, v42, v44
	v_div_fixup_f32 v33, v40, v38, v33
	v_mul_f32_e32 v25, v25, v33
	v_lshlrev_b32_e32 v33, 16, v39
	v_mul_f32_e32 v26, v26, v33
	v_lshlrev_b32_e32 v33, 16, v41
	v_mul_f32_e32 v38, 0xbfb8aa3b, v33
	v_exp_f32_e32 v38, v38
	v_cvt_pk_bf16_f32 v24, v24, v25
	s_nop 0
	v_add_f32_e32 v38, 1.0, v38
	v_div_scale_f32 v40, s[0:1], v38, v38, v33
	v_rcp_f32_e32 v42, v40
	s_nop 0
	v_fma_f32 v43, -v40, v42, 1.0
	v_fmac_f32_e32 v42, v43, v42
	v_div_scale_f32 v43, vcc, v33, v38, v33
	v_mul_f32_e32 v44, v43, v42
	v_fma_f32 v45, -v40, v44, v43
	v_fmac_f32_e32 v44, v45, v42
	v_fma_f32 v40, -v40, v44, v43
	v_div_fmas_f32 v40, v40, v42, v44
	v_div_fixup_f32 v33, v40, v38, v33
	v_mul_f32_e32 v26, v26, v33
	v_and_b32_e32 v33, 0xffff0000, v39
	v_mul_f32_e32 v27, v27, v33
	v_and_b32_e32 v33, 0xffff0000, v41
	v_mul_f32_e32 v38, 0xbfb8aa3b, v33
	v_exp_f32_e32 v38, v38
	s_nop 0
	v_add_f32_e32 v38, 1.0, v38
	v_div_scale_f32 v39, s[0:1], v38, v38, v33
	v_rcp_f32_e32 v40, v39
	s_nop 0
	v_fma_f32 v41, -v39, v40, 1.0
	v_fmac_f32_e32 v40, v41, v40
	v_div_scale_f32 v41, vcc, v33, v38, v33
	v_mul_f32_e32 v42, v41, v40
	v_fma_f32 v43, -v39, v42, v41
	v_fmac_f32_e32 v42, v43, v40
	v_fma_f32 v39, -v39, v42, v41
	v_div_fmas_f32 v39, v39, v40, v42
	v_div_fixup_f32 v33, v39, v38, v33
	v_mul_f32_e32 v27, v27, v33
	v_cvt_pk_bf16_f32 v25, v26, v27
	v_lshl_add_u64 v[26:27], v[28:29], 0, v[2:3]
	global_store_dwordx2 v[26:27], v[24:25], off
	s_nop 0
	s_waitcnt vmcnt(14)
	v_mov_b32_e32 v24, v188
	v_mov_b32_e32 v25, v189
	v_lshlrev_b32_e32 v30, 16, v24
	v_mul_f32_e32 v20, v20, v30
	s_waitcnt vmcnt(13)
	v_mov_b32_e32 v26, v214
	v_mov_b32_e32 v27, v215
	v_lshlrev_b32_e32 v30, 16, v26
	v_mul_f32_e32 v31, 0xbfb8aa3b, v30
	v_exp_f32_e32 v31, v31
	v_and_b32_e32 v24, 0xffff0000, v24
	v_mul_f32_e32 v21, v21, v24
	v_and_b32_e32 v24, 0xffff0000, v26
	v_add_f32_e32 v31, 1.0, v31
	v_div_scale_f32 v33, s[0:1], v31, v31, v30
	v_rcp_f32_e32 v34, v33
	v_mul_f32_e32 v26, 0xbfb8aa3b, v24
	v_exp_f32_e32 v26, v26
	v_fma_f32 v35, -v33, v34, 1.0
	v_fmac_f32_e32 v34, v35, v34
	v_div_scale_f32 v35, vcc, v30, v31, v30
	v_mul_f32_e32 v38, v35, v34
	v_fma_f32 v39, -v33, v38, v35
	v_fmac_f32_e32 v38, v39, v34
	v_fma_f32 v33, -v33, v38, v35
	v_div_fmas_f32 v33, v33, v34, v38
	v_div_fixup_f32 v30, v33, v31, v30
	v_add_f32_e32 v26, 1.0, v26
	v_mul_f32_e32 v20, v20, v30
	v_div_scale_f32 v30, s[0:1], v26, v26, v24
	v_rcp_f32_e32 v31, v30
	s_nop 0
	v_fma_f32 v33, -v30, v31, 1.0
	v_fmac_f32_e32 v31, v33, v31
	v_div_scale_f32 v33, vcc, v24, v26, v24
	v_mul_f32_e32 v34, v33, v31
	v_fma_f32 v35, -v30, v34, v33
	v_fmac_f32_e32 v34, v35, v31
	v_fma_f32 v30, -v30, v34, v33
	v_div_fmas_f32 v30, v30, v31, v34
	v_div_fixup_f32 v24, v30, v26, v24
	v_mul_f32_e32 v21, v21, v24
	v_lshlrev_b32_e32 v24, 16, v25
	v_mul_f32_e32 v22, v22, v24
	v_lshlrev_b32_e32 v24, 16, v27
	v_mul_f32_e32 v26, 0xbfb8aa3b, v24
	v_exp_f32_e32 v26, v26
	v_cvt_pk_bf16_f32 v20, v20, v21
	s_nop 0
	v_add_f32_e32 v26, 1.0, v26
	v_div_scale_f32 v30, s[0:1], v26, v26, v24
	v_rcp_f32_e32 v31, v30
	s_nop 0
	v_fma_f32 v33, -v30, v31, 1.0
	v_fmac_f32_e32 v31, v33, v31
	v_div_scale_f32 v33, vcc, v24, v26, v24
	v_mul_f32_e32 v34, v33, v31
	v_fma_f32 v35, -v30, v34, v33
	v_fmac_f32_e32 v34, v35, v31
	v_fma_f32 v30, -v30, v34, v33
	v_div_fmas_f32 v30, v30, v31, v34
	v_div_fixup_f32 v24, v30, v26, v24
	v_mul_f32_e32 v22, v22, v24
	v_and_b32_e32 v24, 0xffff0000, v25
	v_mul_f32_e32 v23, v23, v24
	v_and_b32_e32 v24, 0xffff0000, v27
	v_mul_f32_e32 v25, 0xbfb8aa3b, v24
	v_exp_f32_e32 v25, v25
	s_nop 0
	v_add_f32_e32 v25, 1.0, v25
	v_div_scale_f32 v26, s[0:1], v25, v25, v24
	v_rcp_f32_e32 v27, v26
	s_nop 0
	v_fma_f32 v30, -v26, v27, 1.0
	v_fmac_f32_e32 v27, v30, v27
	v_div_scale_f32 v30, vcc, v24, v25, v24
	v_mul_f32_e32 v31, v30, v27
	v_fma_f32 v32, -v26, v31, v30
	v_fmac_f32_e32 v31, v32, v27
	v_fma_f32 v26, -v26, v31, v30
	v_div_fmas_f32 v26, v26, v27, v31
	v_div_fixup_f32 v24, v26, v25, v24
	v_mul_f32_e32 v23, v23, v24
	v_cvt_pk_bf16_f32 v21, v22, v23
	v_lshl_add_u64 v[22:23], v[28:29], 0, v[60:61]
	global_store_dwordx2 v[22:23], v[20:21], off
	v_add_u32_e32 v20, 0x60, v0
	v_mov_b32_e32 v21, v1
	v_lshlrev_b64 v[22:23], 11, v[20:21]
	v_lshl_add_u64 v[26:27], s[86:87], 0, v[22:23]
	v_lshl_add_u64 v[22:23], s[34:35], 0, v[22:23]
	v_lshl_add_u64 v[26:27], v[26:27], 0, v[2:3]
	v_lshl_add_u64 v[22:23], v[22:23], 0, v[2:3]
	v_lshlrev_b64 v[20:21], 12, v[20:21]
	v_lshl_add_u64 v[20:21], s[58:59], 0, v[20:21]
	v_lshl_add_u64 v[20:21], v[20:21], 0, s[6:7]
	v_add_u32_e32 v0, 0x70, v0
	s_waitcnt vmcnt(13)
; __device__ __forceinline__ unsigned cvt_pk_bf16(float lo, float hi) { unsigned r; asm("v_cvt_pk_bf16_f32 %0, %1, %2" : "=v"(r) : "v"(lo), "v"(hi)); return r; }
; __device__ __forceinline__ float bflo(unsigned w) { return __uint_as_float(w << 16); }
; __device__ __forceinline__ float bfhi(unsigned w) { return __uint_as_float(w & 0xffff0000u); }
; __device__ __forceinline__ float silu(float x) { return x / (1.f + __expf(-x)); }
; __device__ __forceinline__ void gmlp_item(const Params& p, int l, int mc, int g, LAS unsigned char* lds) {
;     ...
;     const float* bsp = p.b_s + (size_t)(l * 4 + g) * 128;
; #pragma unroll
;     for (int tt = 0; tt < 8; ++tt) {
;         if (tt < ntt) {
;             const int tok = tok0 + tt * 16 + fr; const float bs = bsp[tt * 16 + fr];
; #pragma unroll
;             for (int ct = 0; ct < 2; ++ct) {
;                 const int cb = g * 256 + w * 32 + ct * 16 + fq * 4;
;                 const u32x2 uu = *(const u32x2*)((const u16*)(ws + WS_ZU) + (size_t)tok * 1024 + cb);
;                 const u32x2 gg = *(const u32x2*)((const u16*)(ws + WS_ZGB) + (size_t)tok * 1024 + cb);
;                 const float o0 = bflo(uu.x) * (acc[ct][tt][0] + bs) * silu(bflo(gg.x));
;                 const float o1 = bfhi(uu.x) * (acc[ct][tt][1] + bs) * silu(bfhi(gg.x));
;                 const float o2 = bflo(uu.y) * (acc[ct][tt][2] + bs) * silu(bflo(gg.y));
;                 const float o3 = bfhi(uu.y) * (acc[ct][tt][3] + bs) * silu(bfhi(gg.y));
;                 u32x2 wv; wv.x = cvt_pk_bf16(o0, o1); wv.y = cvt_pk_bf16(o2, o3);
;                 *(u32x2*)((u16*)(ws + WS_OBUF) + (size_t)tok * 2048 + 1024 + cb) = wv;
;             }
;         }
;     }
	v_mov_b32_e32 v24, v180
	v_add_f32_e32 v16, v16, v24
	s_waitcnt vmcnt(12)
	v_mov_b32_e32 v28, v190
	v_mov_b32_e32 v29, v191
	v_lshlrev_b32_e32 v25, 16, v28
	v_mul_f32_e32 v16, v16, v25
	s_waitcnt vmcnt(11)
	v_mov_b32_e32 v30, v216
	v_mov_b32_e32 v31, v217
	v_lshlrev_b32_e32 v25, 16, v30
	v_mul_f32_e32 v32, 0xbfb8aa3b, v25
	v_exp_f32_e32 v32, v32
	v_add_f32_e32 v17, v17, v24
	v_add_f32_e32 v18, v18, v24
	v_add_f32_e32 v19, v19, v24
	v_add_f32_e32 v32, 1.0, v32
	v_div_scale_f32 v33, s[0:1], v32, v32, v25
	v_rcp_f32_e32 v34, v33
	v_add_f32_e32 v12, v12, v24
	v_add_f32_e32 v13, v13, v24
	v_add_f32_e32 v14, v14, v24
	v_fma_f32 v35, -v33, v34, 1.0
	v_fmac_f32_e32 v34, v35, v34
	v_div_scale_f32 v35, vcc, v25, v32, v25
	v_mul_f32_e32 v38, v35, v34
	v_fma_f32 v39, -v33, v38, v35
	v_fmac_f32_e32 v38, v39, v34
	v_fma_f32 v33, -v33, v38, v35
	v_div_fmas_f32 v33, v33, v34, v38
	v_div_fixup_f32 v25, v33, v32, v25
	v_mul_f32_e32 v16, v16, v25
	v_and_b32_e32 v25, 0xffff0000, v28
	v_mul_f32_e32 v17, v17, v25
	v_and_b32_e32 v25, 0xffff0000, v30
	v_mul_f32_e32 v28, 0xbfb8aa3b, v25
	v_exp_f32_e32 v28, v28
	v_add_f32_e32 v15, v15, v24
	v_add_f32_e32 v28, 1.0, v28
	v_div_scale_f32 v30, s[0:1], v28, v28, v25
	v_rcp_f32_e32 v32, v30
	s_nop 0
	v_fma_f32 v33, -v30, v32, 1.0
	v_fmac_f32_e32 v32, v33, v32
	v_div_scale_f32 v33, vcc, v25, v28, v25
	v_mul_f32_e32 v34, v33, v32
	v_fma_f32 v35, -v30, v34, v33
	v_fmac_f32_e32 v34, v35, v32
	v_fma_f32 v30, -v30, v34, v33
	v_div_fmas_f32 v30, v30, v32, v34
	v_div_fixup_f32 v25, v30, v28, v25
	v_mul_f32_e32 v17, v17, v25
	v_lshlrev_b32_e32 v25, 16, v29
	v_mul_f32_e32 v18, v18, v25
	v_lshlrev_b32_e32 v25, 16, v31
	v_mul_f32_e32 v28, 0xbfb8aa3b, v25
	v_exp_f32_e32 v28, v28
	v_cvt_pk_bf16_f32 v16, v16, v17
	s_nop 0
	v_add_f32_e32 v28, 1.0, v28
	v_div_scale_f32 v30, s[0:1], v28, v28, v25
	v_rcp_f32_e32 v32, v30
	s_nop 0
	v_fma_f32 v33, -v30, v32, 1.0
	v_fmac_f32_e32 v32, v33, v32
	v_div_scale_f32 v33, vcc, v25, v28, v25
	v_mul_f32_e32 v34, v33, v32
	v_fma_f32 v35, -v30, v34, v33
	v_fmac_f32_e32 v34, v35, v32
	v_fma_f32 v30, -v30, v34, v33
	v_div_fmas_f32 v30, v30, v32, v34
	v_div_fixup_f32 v25, v30, v28, v25
	v_mul_f32_e32 v18, v18, v25
	v_and_b32_e32 v25, 0xffff0000, v29
	v_mul_f32_e32 v19, v19, v25
	v_and_b32_e32 v25, 0xffff0000, v31
	v_mul_f32_e32 v28, 0xbfb8aa3b, v25
	v_exp_f32_e32 v28, v28
	s_nop 0
	v_add_f32_e32 v28, 1.0, v28
	v_div_scale_f32 v29, s[0:1], v28, v28, v25
	v_rcp_f32_e32 v30, v29
	s_nop 0
	v_fma_f32 v31, -v29, v30, 1.0
	v_fmac_f32_e32 v30, v31, v30
	v_div_scale_f32 v31, vcc, v25, v28, v25
	v_mul_f32_e32 v32, v31, v30
	v_fma_f32 v33, -v29, v32, v31
	v_fmac_f32_e32 v32, v33, v30
	v_fma_f32 v29, -v29, v32, v31
	v_div_fmas_f32 v29, v29, v30, v32
	v_div_fixup_f32 v25, v29, v28, v25
	v_mul_f32_e32 v19, v19, v25
	v_cvt_pk_bf16_f32 v17, v18, v19
	v_lshl_add_u64 v[18:19], v[20:21], 0, v[2:3]
	global_store_dwordx2 v[18:19], v[16:17], off
	s_nop 0
	s_waitcnt vmcnt(11)
	v_mov_b32_e32 v16, v192
	v_mov_b32_e32 v17, v193
	v_lshlrev_b32_e32 v22, 16, v16
	v_mul_f32_e32 v12, v12, v22
	s_waitcnt vmcnt(10)
	v_mov_b32_e32 v18, v218
	v_mov_b32_e32 v19, v219
	v_lshlrev_b32_e32 v22, 16, v18
	v_mul_f32_e32 v23, 0xbfb8aa3b, v22
	v_exp_f32_e32 v23, v23
	v_and_b32_e32 v16, 0xffff0000, v16
	v_mul_f32_e32 v13, v13, v16
	v_and_b32_e32 v16, 0xffff0000, v18
	v_add_f32_e32 v23, 1.0, v23
	v_div_scale_f32 v25, s[0:1], v23, v23, v22
	v_rcp_f32_e32 v26, v25
	v_mul_f32_e32 v18, 0xbfb8aa3b, v16
	v_exp_f32_e32 v18, v18
	v_fma_f32 v27, -v25, v26, 1.0
	v_fmac_f32_e32 v26, v27, v26
	v_div_scale_f32 v27, vcc, v22, v23, v22
	v_mul_f32_e32 v28, v27, v26
	v_fma_f32 v29, -v25, v28, v27
	v_fmac_f32_e32 v28, v29, v26
	v_fma_f32 v25, -v25, v28, v27
	v_div_fmas_f32 v25, v25, v26, v28
	v_div_fixup_f32 v22, v25, v23, v22
	v_add_f32_e32 v18, 1.0, v18
	v_mul_f32_e32 v12, v12, v22
	v_div_scale_f32 v22, s[0:1], v18, v18, v16
	v_rcp_f32_e32 v23, v22
	s_nop 0
	v_fma_f32 v25, -v22, v23, 1.0
	v_fmac_f32_e32 v23, v25, v23
	v_div_scale_f32 v25, vcc, v16, v18, v16
	v_mul_f32_e32 v26, v25, v23
	v_fma_f32 v27, -v22, v26, v25
	v_fmac_f32_e32 v26, v27, v23
	v_fma_f32 v22, -v22, v26, v25
	v_div_fmas_f32 v22, v22, v23, v26
	v_div_fixup_f32 v16, v22, v18, v16
	v_mul_f32_e32 v13, v13, v16
	v_lshlrev_b32_e32 v16, 16, v17
	v_mul_f32_e32 v14, v14, v16
	v_lshlrev_b32_e32 v16, 16, v19
	v_mul_f32_e32 v18, 0xbfb8aa3b, v16
	v_exp_f32_e32 v18, v18
	v_cvt_pk_bf16_f32 v12, v12, v13
	s_nop 0
	v_add_f32_e32 v18, 1.0, v18
	v_div_scale_f32 v22, s[0:1], v18, v18, v16
	v_rcp_f32_e32 v23, v22
	s_nop 0
	v_fma_f32 v25, -v22, v23, 1.0
	v_fmac_f32_e32 v23, v25, v23
	v_div_scale_f32 v25, vcc, v16, v18, v16
	v_mul_f32_e32 v26, v25, v23
	v_fma_f32 v27, -v22, v26, v25
	v_fmac_f32_e32 v26, v27, v23
	v_fma_f32 v22, -v22, v26, v25
	v_div_fmas_f32 v22, v22, v23, v26
	v_div_fixup_f32 v16, v22, v18, v16
	v_mul_f32_e32 v14, v14, v16
	v_and_b32_e32 v16, 0xffff0000, v17
	v_mul_f32_e32 v15, v15, v16
	v_and_b32_e32 v16, 0xffff0000, v19
	v_mul_f32_e32 v17, 0xbfb8aa3b, v16
	v_exp_f32_e32 v17, v17
	s_nop 0
	v_add_f32_e32 v17, 1.0, v17
	v_div_scale_f32 v18, s[0:1], v17, v17, v16
	v_rcp_f32_e32 v19, v18
	s_nop 0
	v_fma_f32 v22, -v18, v19, 1.0
	v_fmac_f32_e32 v19, v22, v19
	v_div_scale_f32 v22, vcc, v16, v17, v16
	v_mul_f32_e32 v23, v22, v19
	v_fma_f32 v24, -v18, v23, v22
	v_fmac_f32_e32 v23, v24, v19
	v_fma_f32 v18, -v18, v23, v22
	v_div_fmas_f32 v18, v18, v19, v23
	v_div_fixup_f32 v16, v18, v17, v16
	v_mul_f32_e32 v15, v15, v16
	v_cvt_pk_bf16_f32 v13, v14, v15
	v_lshl_add_u64 v[14:15], v[20:21], 0, v[60:61]
	global_store_dwordx2 v[14:15], v[12:13], off
	v_lshlrev_b64 v[12:13], 11, v[0:1]
	v_lshl_add_u64 v[14:15], s[86:87], 0, v[12:13]
	v_lshl_add_u64 v[18:19], s[34:35], 0, v[12:13]
	v_lshl_add_u64 v[20:21], v[14:15], 0, v[2:3]
	v_lshl_add_u64 v[14:15], v[18:19], 0, v[2:3]
	v_lshlrev_b64 v[12:13], 12, v[0:1]
	v_lshl_add_u64 v[12:13], s[58:59], 0, v[12:13]
	v_lshl_add_u64 v[12:13], v[12:13], 0, s[6:7]
	v_lshl_add_u64 v[2:3], v[12:13], 0, v[2:3]
	s_waitcnt vmcnt(10)
; __device__ __forceinline__ unsigned cvt_pk_bf16(float lo, float hi) { unsigned r; asm("v_cvt_pk_bf16_f32 %0, %1, %2" : "=v"(r) : "v"(lo), "v"(hi)); return r; }
; __device__ __forceinline__ float bflo(unsigned w) { return __uint_as_float(w << 16); }
; __device__ __forceinline__ float bfhi(unsigned w) { return __uint_as_float(w & 0xffff0000u); }
; __device__ __forceinline__ float silu(float x) { return x / (1.f + __expf(-x)); }
; __device__ __forceinline__ void gmlp_item(const Params& p, int l, int mc, int g, LAS unsigned char* lds) {
;     ...
;     const float* bsp = p.b_s + (size_t)(l * 4 + g) * 128;
; #pragma unroll
;     for (int tt = 0; tt < 8; ++tt) {
;         if (tt < ntt) {
;             const int tok = tok0 + tt * 16 + fr; const float bs = bsp[tt * 16 + fr];
; #pragma unroll
;             for (int ct = 0; ct < 2; ++ct) {
;                 const int cb = g * 256 + w * 32 + ct * 16 + fq * 4;
;                 const u32x2 uu = *(const u32x2*)((const u16*)(ws + WS_ZU) + (size_t)tok * 1024 + cb);
;                 const u32x2 gg = *(const u32x2*)((const u16*)(ws + WS_ZGB) + (size_t)tok * 1024 + cb);
;                 const float o0 = bflo(uu.x) * (acc[ct][tt][0] + bs) * silu(bflo(gg.x));
;                 const float o1 = bfhi(uu.x) * (acc[ct][tt][1] + bs) * silu(bfhi(gg.x));
;                 const float o2 = bflo(uu.y) * (acc[ct][tt][2] + bs) * silu(bflo(gg.y));
;                 const float o3 = bfhi(uu.y) * (acc[ct][tt][3] + bs) * silu(bfhi(gg.y));
;                 u32x2 wv; wv.x = cvt_pk_bf16(o0, o1); wv.y = cvt_pk_bf16(o2, o3);
;                 *(u32x2*)((u16*)(ws + WS_OBUF) + (size_t)tok * 2048 + 1024 + cb) = wv;
;             }
;         }
;     }
	v_mov_b32_e32 v16, v181
	v_add_f32_e32 v8, v8, v16
	s_waitcnt vmcnt(9)
	v_mov_b32_e32 v22, v194
	v_mov_b32_e32 v23, v195
	v_lshlrev_b32_e32 v0, 16, v22
	v_mul_f32_e32 v0, v8, v0
	s_waitcnt vmcnt(8)
	v_mov_b32_e32 v18, v220
	v_mov_b32_e32 v19, v221
	v_lshlrev_b32_e32 v8, 16, v18
	v_mul_f32_e32 v17, 0xbfb8aa3b, v8
	v_exp_f32_e32 v17, v17
	v_add_f32_e32 v9, v9, v16
	v_add_f32_e32 v10, v10, v16
	v_add_f32_e32 v11, v11, v16
	v_add_f32_e32 v17, 1.0, v17
	v_div_scale_f32 v24, s[0:1], v17, v17, v8
	v_rcp_f32_e32 v25, v24
	v_add_f32_e32 v4, v4, v16
	v_fma_f32 v26, -v24, v25, 1.0
	v_fmac_f32_e32 v25, v26, v25
	v_div_scale_f32 v26, vcc, v8, v17, v8
	v_mul_f32_e32 v27, v26, v25
	v_fma_f32 v28, -v24, v27, v26
	v_fmac_f32_e32 v27, v28, v25
	v_fma_f32 v24, -v24, v27, v26
	v_div_fmas_f32 v24, v24, v25, v27
	v_div_fixup_f32 v8, v24, v17, v8
	v_mul_f32_e32 v0, v0, v8
	v_and_b32_e32 v8, 0xffff0000, v22
	v_mul_f32_e32 v8, v9, v8
	v_and_b32_e32 v9, 0xffff0000, v18
	v_mul_f32_e32 v17, 0xbfb8aa3b, v9
	v_exp_f32_e32 v17, v17
	s_nop 0
	v_add_f32_e32 v17, 1.0, v17
	v_div_scale_f32 v18, s[0:1], v17, v17, v9
	v_rcp_f32_e32 v22, v18
	s_nop 0
	v_fma_f32 v24, -v18, v22, 1.0
	v_fmac_f32_e32 v22, v24, v22
	v_div_scale_f32 v24, vcc, v9, v17, v9
	v_mul_f32_e32 v25, v24, v22
	v_fma_f32 v26, -v18, v25, v24
	v_fmac_f32_e32 v25, v26, v22
	v_fma_f32 v18, -v18, v25, v24
	v_div_fmas_f32 v18, v18, v22, v25
	v_div_fixup_f32 v9, v18, v17, v9
	v_mul_f32_e32 v8, v8, v9
	v_lshlrev_b32_e32 v9, 16, v23
	v_mul_f32_e32 v9, v10, v9
	v_lshlrev_b32_e32 v10, 16, v19
	v_mul_f32_e32 v17, 0xbfb8aa3b, v10
	v_exp_f32_e32 v17, v17
	v_cvt_pk_bf16_f32 v8, v0, v8
	s_nop 0
	v_add_f32_e32 v17, 1.0, v17
	v_div_scale_f32 v18, s[0:1], v17, v17, v10
	v_rcp_f32_e32 v22, v18
	s_nop 0
	v_fma_f32 v24, -v18, v22, 1.0
	v_fmac_f32_e32 v22, v24, v22
	v_div_scale_f32 v24, vcc, v10, v17, v10
	v_mul_f32_e32 v25, v24, v22
	v_fma_f32 v26, -v18, v25, v24
	v_fmac_f32_e32 v25, v26, v22
	v_fma_f32 v18, -v18, v25, v24
	v_div_fmas_f32 v18, v18, v22, v25
	v_div_fixup_f32 v10, v18, v17, v10
	v_mul_f32_e32 v9, v9, v10
	v_and_b32_e32 v10, 0xffff0000, v23
	v_mul_f32_e32 v10, v11, v10
	v_and_b32_e32 v11, 0xffff0000, v19
	v_mul_f32_e32 v17, 0xbfb8aa3b, v11
	v_exp_f32_e32 v17, v17
	s_nop 0
	v_add_f32_e32 v17, 1.0, v17
	v_div_scale_f32 v18, s[0:1], v17, v17, v11
	v_rcp_f32_e32 v19, v18
	s_nop 0
	v_fma_f32 v22, -v18, v19, 1.0
	v_fmac_f32_e32 v19, v22, v19
	v_div_scale_f32 v22, vcc, v11, v17, v11
	v_mul_f32_e32 v23, v22, v19
	v_fma_f32 v24, -v18, v23, v22
	v_fmac_f32_e32 v23, v24, v19
	v_fma_f32 v18, -v18, v23, v22
	v_div_fmas_f32 v18, v18, v19, v23
	v_div_fixup_f32 v11, v18, v17, v11
	v_mul_f32_e32 v10, v10, v11
	v_cvt_pk_bf16_f32 v9, v9, v10
	global_store_dwordx2 v[2:3], v[8:9], off
	s_nop 0
	s_waitcnt vmcnt(8)
	v_mov_b32_e32 v2, v196
	v_mov_b32_e32 v3, v197
	v_lshlrev_b32_e32 v0, 16, v2
	v_mul_f32_e32 v0, v4, v0
	s_waitcnt vmcnt(7)
	v_mov_b32_e32 v8, v222
	v_mov_b32_e32 v9, v223
	v_lshlrev_b32_e32 v4, 16, v8
	v_mul_f32_e32 v10, 0xbfb8aa3b, v4
	v_exp_f32_e32 v10, v10
	v_and_b32_e32 v2, 0xffff0000, v2
	v_add_f32_e32 v10, 1.0, v10
	v_div_scale_f32 v11, s[0:1], v10, v10, v4
	v_rcp_f32_e32 v14, v11
	s_nop 0
	v_fma_f32 v15, -v11, v14, 1.0
	v_fmac_f32_e32 v14, v15, v14
	v_div_scale_f32 v15, vcc, v4, v10, v4
	v_mul_f32_e32 v17, v15, v14
	v_fma_f32 v18, -v11, v17, v15
	v_fmac_f32_e32 v17, v18, v14
	v_fma_f32 v11, -v11, v17, v15
	v_div_fmas_f32 v11, v11, v14, v17
	v_div_fixup_f32 v4, v11, v10, v4
	v_mul_f32_e32 v0, v0, v4
	v_add_f32_e32 v4, v5, v16
	v_mul_f32_e32 v2, v4, v2
	v_and_b32_e32 v4, 0xffff0000, v8
	v_mul_f32_e32 v5, 0xbfb8aa3b, v4
	v_exp_f32_e32 v5, v5
	s_nop 0
	v_add_f32_e32 v5, 1.0, v5
	v_div_scale_f32 v8, s[0:1], v5, v5, v4
	v_rcp_f32_e32 v10, v8
	s_nop 0
	v_fma_f32 v11, -v8, v10, 1.0
	v_fmac_f32_e32 v10, v11, v10
	v_div_scale_f32 v11, vcc, v4, v5, v4
	v_mul_f32_e32 v14, v11, v10
	v_fma_f32 v15, -v8, v14, v11
	v_fmac_f32_e32 v14, v15, v10
	v_fma_f32 v8, -v8, v14, v11
	v_div_fmas_f32 v8, v8, v10, v14
	v_div_fixup_f32 v4, v8, v5, v4
	v_mul_f32_e32 v2, v2, v4
	v_lshlrev_b32_e32 v4, 16, v3
	v_add_f32_e32 v5, v6, v16
	v_mul_f32_e32 v4, v5, v4
	v_lshlrev_b32_e32 v5, 16, v9
	v_mul_f32_e32 v6, 0xbfb8aa3b, v5
	v_exp_f32_e32 v6, v6
	v_and_b32_e32 v3, 0xffff0000, v3
	v_cvt_pk_bf16_f32 v2, v0, v2
	v_add_f32_e32 v6, 1.0, v6
	v_div_scale_f32 v8, s[0:1], v6, v6, v5
	v_rcp_f32_e32 v10, v8
	s_nop 0
	v_fma_f32 v11, -v8, v10, 1.0
	v_fmac_f32_e32 v10, v11, v10
	v_div_scale_f32 v11, vcc, v5, v6, v5
	v_mul_f32_e32 v14, v11, v10
	v_fma_f32 v15, -v8, v14, v11
	v_fmac_f32_e32 v14, v15, v10
	v_fma_f32 v8, -v8, v14, v11
	v_div_fmas_f32 v8, v8, v10, v14
	v_div_fixup_f32 v5, v8, v6, v5
	v_mul_f32_e32 v4, v4, v5
	v_add_f32_e32 v5, v7, v16
	v_mul_f32_e32 v3, v5, v3
	v_and_b32_e32 v5, 0xffff0000, v9
	v_mul_f32_e32 v6, 0xbfb8aa3b, v5
	v_exp_f32_e32 v6, v6
	s_nop 0
	v_add_f32_e32 v6, 1.0, v6
	v_div_scale_f32 v7, s[0:1], v6, v6, v5
	v_rcp_f32_e32 v8, v7
	s_nop 0
	v_fma_f32 v9, -v7, v8, 1.0
	v_fmac_f32_e32 v8, v9, v8
	v_div_scale_f32 v9, vcc, v5, v6, v5
	v_mul_f32_e32 v10, v9, v8
	v_fma_f32 v11, -v7, v10, v9
	v_fmac_f32_e32 v10, v11, v8
	v_fma_f32 v7, -v7, v10, v9
	v_div_fmas_f32 v7, v7, v8, v10
	v_div_fixup_f32 v5, v7, v6, v5
	v_mul_f32_e32 v3, v3, v5
	v_cvt_pk_bf16_f32 v3, v4, v3
	v_lshl_add_u64 v[4:5], v[12:13], 0, v[60:61]
	global_store_dwordx2 v[4:5], v[2:3], off
